# hand-rewritten RWKV scan item: all 4 waves do recurrence+y for 4 rows, deferred transposing y reduction, 2 LDS buffers
# speedup vs baseline: 1.1135x; 1.1135x over previous
; __device__ __forceinline__ float bf2f(unsigned short b) { return __uint_as_float(((unsigned)b) << 16); }
; __device__ __forceinline__ void rwkv_scan2_item(const Params& p, int item, char* ldsraw) {
;   const float* RW = (const float*)(WS(p) + OFF_RW); const bf16_t* RB = (const bf16_t*)(WS(p) + OFF_RB); const float* RC = (const float*)(WS(p) + OFF_RC);
;   bf16_t* Yb = (bf16_t*)(WS(p) + OFF_Y);
;   float* buf = (float*)ldsraw;
;   constexpr int STEP = 340, CH = 16 * STEP;
;   float* SA = buf + 3 * CH;
;   const int bh = item / 12, rr = item - bh * 12, b = bh >> 2, h = bh & 3;
;   const int seg = (rr >= 4) ? 1 : 0, ident = (rr >= 8) ? 1 : 0, r16 = rr & 3;
;   const int c0 = seg * 128;
;   const int tid = opaque_tid(), lane = tid & 63, wid = tid >> 6, jl = lane & 15, rl = lane >> 4;
;   const int isY = wid >> 1, row8 = (wid & 1) * 4 + rl;
;   const int rowA = r16 * 16 + row8;
;   const int st = tid >> 4, part = tid & 15;
;   f32x4 pw; u32x2 pkk, pkka, pk, pwr; unsigned short pv; float pc;
;   auto load = [&](int chunk) {
;     const size_t base = (size_t)bh * S + chunk * 16 + st;
;     pw = *(const f32x4*)(RW + base * 64 + part * 4);
;     const bf16_t* rb = RB + base * 320;
;     pkk = *(const u32x2*)(rb + part * 4); pkka = *(const u32x2*)(rb + 64 + part * 4);
;     pk = *(const u32x2*)(rb + 128 + part * 4); pwr = *(const u32x2*)(rb + 192 + part * 4);
;     pv = rb[256 + r16 * 16 + part];
;     pc = (part < 2) ? RC[base * 4 + part] : 0.f;
;   };
;   auto store = [&](int bi) {
;     float* d = buf + bi * CH + st * STEP;
;     *(f32x4*)(d + part * 4) = pw;
;     *(f32x4*)(d + 64 + part * 4) = (f32x4){bflo(pkk[0]), bfhi(pkk[0]), bflo(pkk[1]), bfhi(pkk[1])};
;     *(f32x4*)(d + 128 + part * 4) = (f32x4){bflo(pkka[0]), bfhi(pkka[0]), bflo(pkka[1]), bfhi(pkka[1])};
;     *(f32x4*)(d + 192 + part * 4) = (f32x4){bflo(pk[0]), bfhi(pk[0]), bflo(pk[1]), bfhi(pk[1])};
;     *(f32x4*)(d + 256 + part * 4) = (f32x4){bflo(pwr[0]), bfhi(pwr[0]), bflo(pwr[1]), bfhi(pwr[1])};
;     d[320 + part] = ident ? 0.f : bf2f(pv);
;     if (part < 2) d[336 + part] = pc;
;   };
;   load(c0); store(0); __syncthreads();
;   float a0 = 0.f, a1 = 0.f, a2 = 0.f, a3 = 0.f, b0 = 0.f, b1 = 0.f, b2 = 0.f, b3 = 0.f;
;   if (ident) {
;     const int mA = rowA - jl * 4, mB = mA + 8;
;     a0 = (mA == 0) ? 1.f : 0.f; a1 = (mA == 1) ? 1.f : 0.f; a2 = (mA == 2) ? 1.f : 0.f; a3 = (mA == 3) ? 1.f : 0.f;
.LBB0_478:
	s_andn2_b64 vcc, exec, s[24:25]
	s_cbranch_vccnz .LBB0_157
	s_mul_i32 s2, s78, 0xaaab
	s_lshr_b32 s2, s2, 19
	s_mul_i32 s3, s2, 12
	s_sub_u32 s3, s78, s3
	s_and_b32 s4, s3, 3
	s_lshr_b32 s41, s3, 2
	s_cmp_lg_u32 s41, 0
	s_cselect_b32 s42, 0x800, 0
	s_lshl_b32 s88, s2, 12
	s_add_u32 s88, s88, s42
	s_lshl_b32 s24, s88, 8
	s_add_u32 s24, s24, 0x87a8000
	s_add_u32 s24, s46, s24
	s_addc_u32 s25, s47, 0
	s_mul_i32 s26, s88, 640
	s_add_u32 s26, s26, 0x97a8000
	s_add_u32 s26, s46, s26
	s_addc_u32 s27, s47, 0
	s_lshl_b32 s28, s88, 4
	s_add_u32 s28, s28, 0xbfa8000
	s_add_u32 s28, s46, s28
	s_addc_u32 s29, s47, 0
	s_lshr_b32 s30, s2, 2
	s_lshl_b32 s30, s30, 12
	s_add_u32 s30, s30, s42
	s_lshl_b32 s30, s30, 11
	s_and_b32 s88, s2, 3
	s_lshl_b32 s88, s88, 7
	s_add_u32 s30, s30, s88
	s_add_u32 s30, s30, 0xc0a8400
	s_lshl_b32 s88, s2, 18
	s_add_u32 s88, s88, 0xfb4c000
	s_cmp_eq_u32 s41, 2
	s_cselect_b32 s30, s88, s30
	s_mov_b32 s40, 0x8000
	s_cselect_b32 s40, 0x800, s40
	s_cselect_b32 s88, 7, 11
	s_add_u32 s30, s46, s30
	s_addc_u32 s31, s47, 0
	s_mov_b32 s34, 0xaaaaaaaa
	s_mov_b32 s35, 0xaaaaaaaa
	s_mov_b32 s36, 0xcccccccc
	s_mov_b32 s37, 0xcccccccc
	v_and_b32_e32 v17, 15, v198
	v_lshrrev_b32_e32 v18, 4, v198
	v_and_b32_e32 v18, 15, v18
	v_bfrev_b32_e32 v19, v17
	v_lshrrev_b32_e32 v19, 28, v19
	v_lshlrev_b32_e32 v0, 4, v17
	v_lshlrev_b32_e32 v1, 6, v18
	v_add_u32_e32 v1, 0x5000, v1
	s_movk_i32 s42, 0x500
	v_mad_u32_u24 v2, v18, s42, v0
	v_lshlrev_b32_e32 v8, 6, v17
	v_lshl_add_u32 v8, v18, 2, v8
	v_add_u32_e32 v8, 0x5000, v8
	v_lshlrev_b32_e32 v9, 3, v18
	v_add_u32_e32 v9, 0x5400, v9
	v_lshl_add_u32 v10, v19, 2, v1
	v_lshlrev_b32_e32 v11, 3, v19
	v_add_u32_e32 v11, 0x5400, v11
	v_lshlrev_b32_e32 v12, 8, v18
	v_add_u32_e32 v12, v12, v0
	s_movk_i32 s42, 0x280
	v_mul_u32_u24_e32 v14, s42, v18
	v_lshl_add_u32 v13, v17, 3, v14
	v_lshl_add_u32 v14, v17, 1, v14
	s_lshl_b32 s42, s4, 5
	s_add_u32 s42, s42, 0x200
	v_add_u32_e32 v14, s42, v14
	v_lshlrev_b32_e32 v15, 4, v18
	s_lshl_b32 s42, s4, 4
	v_add_u32_e32 v18, s42, v18
	v_lshlrev_b32_e32 v16, s88, v19
	v_lshl_add_u32 v16, v18, 1, v16
	v_mov_b32_e32 v4, 0
	v_mov_b32_e32 v5, 0
	v_mov_b32_e32 v6, 0
	v_mov_b32_e32 v7, 0
	v_mov_b32_e32 v108, 0
	v_mov_b32_e32 v109, 0
	v_mov_b32_e32 v110, 0
	v_mov_b32_e32 v111, 0
	s_cmp_lg_u32 s41, 2
	s_cbranch_scc1 .Lsc_noident
	v_lshlrev_b32_e32 v17, 2, v17
	v_sub_u32_e32 v17, v18, v17
	v_cmp_eq_u32_e32 vcc, 0, v17
	s_nop 1
	v_cndmask_b32_e64 v4, 0, 1.0, vcc
	v_cmp_eq_u32_e32 vcc, 1, v17
	s_nop 1
	v_cndmask_b32_e64 v5, 0, 1.0, vcc
	v_cmp_eq_u32_e32 vcc, 2, v17
	s_nop 1
	v_cndmask_b32_e64 v6, 0, 1.0, vcc
	v_cmp_eq_u32_e32 vcc, 3, v17
	s_nop 1
	v_cndmask_b32_e64 v7, 0, 1.0, vcc
.Lsc_noident:
	global_load_dwordx4 v[20:23], v12, s[24:25]
	global_load_dwordx2 v[24:25], v13, s[26:27]
	global_load_dwordx2 v[26:27], v13, s[26:27] offset:128
	global_load_dwordx2 v[28:29], v13, s[26:27] offset:256
	global_load_dwordx2 v[30:31], v13, s[26:27] offset:384
	global_load_ushort v32, v14, s[26:27]
	global_load_dwordx2 v[34:35], v15, s[28:29]
	s_waitcnt vmcnt(0)
	ds_write_b128 v2, v[20:23] offset:0
	v_lshlrev_b32_e32 v36, 16, v24
	v_lshlrev_b32_e32 v37, 16, v30
	v_and_b32_e32 v38, 0xffff0000, v24
	v_and_b32_e32 v39, 0xffff0000, v30
	ds_write_b128 v2, v[36:39] offset:256
	v_lshlrev_b32_e32 v40, 16, v25
	v_lshlrev_b32_e32 v41, 16, v31
	v_and_b32_e32 v42, 0xffff0000, v25
	v_and_b32_e32 v43, 0xffff0000, v31
	ds_write_b128 v2, v[40:43] offset:512
	v_lshlrev_b32_e32 v44, 16, v26
	v_and_b32_e32 v45, 0xffff0000, v26
	v_lshlrev_b32_e32 v46, 16, v27
	v_and_b32_e32 v47, 0xffff0000, v27
	ds_write_b128 v2, v[44:47] offset:768
	v_lshlrev_b32_e32 v48, 16, v28
	v_and_b32_e32 v49, 0xffff0000, v28
	v_lshlrev_b32_e32 v50, 16, v29
	v_and_b32_e32 v51, 0xffff0000, v29
	ds_write_b128 v2, v[48:51] offset:1024
	v_lshlrev_b32_e32 v52, 16, v32
	s_cmp_eq_u32 s41, 2
	s_cselect_b32 s2, 0, -1
	v_and_b32_e32 v52, s2, v52
	ds_write_b32 v8, v52 offset:0
	s_mov_b32 s2, 0x00010001
	s_mov_b32 s3, 0x00010001
	s_mov_b64 exec, s[2:3]
	ds_write_b64 v9, v[34:35] offset:0
	s_mov_b64 exec, -1
	s_add_u32 s24, s24, 0x1000
	s_addc_u32 s25, s25, 0
	s_add_u32 s26, s26, 0x2800
	s_addc_u32 s27, s27, 0
	s_add_u32 s28, s28, 0x100
	s_addc_u32 s29, s29, 0
	s_waitcnt lgkmcnt(0)
	s_barrier
	s_mov_b32 s38, 0
; __device__ __forceinline__ void rwkv_scan2_item(const Params& p, int item, char* ldsraw) {
;     ...
;         for (int q = 0; q < 16; q++) {
;           const f32x4 cw = nw, ckk = nkk, ckka = nkka, ck = nk; const float cvA = nvA, cvB = nvB;
;           if (q < 15) R_LOAD(q + 1)
;           __builtin_amdgcn_sched_barrier(0);
;           float mA0 = mul_s(a0, ckk.x), mA1 = mul_s(a2, ckk.z), mB0 = mul_s(b0, ckk.x), mB1 = mul_s(b2, ckk.z);
;           mA0 = fma_s(a1, ckk.y, mA0); mA1 = fma_s(a3, ckk.w, mA1); mB0 = fma_s(b1, ckk.y, mB0); mB1 = fma_s(b3, ckk.w, mB1);
;           float psA = add_s(mA0, mA1), psB = add_s(mB0, mB1);
;           psA = row16_sum(psA); psB = row16_sum(psB);
;           { const float t0 = fnma_s(psA, ckka.x, mul_s(cvA, ck.x)), t1 = fnma_s(psA, ckka.y, mul_s(cvA, ck.y));
;             const float t2 = fnma_s(psA, ckka.z, mul_s(cvA, ck.z)), t3 = fnma_s(psA, ckka.w, mul_s(cvA, ck.w));
;             a0 = fma_s(a0, cw.x, t0); a1 = fma_s(a1, cw.y, t1); a2 = fma_s(a2, cw.z, t2); a3 = fma_s(a3, cw.w, t3); }
;           { const float t0 = fnma_s(psB, ckka.x, mul_s(cvB, ck.x)), t1 = fnma_s(psB, ckka.y, mul_s(cvB, ck.y));
;             const float t2 = fnma_s(psB, ckka.z, mul_s(cvB, ck.z)), t3 = fnma_s(psB, ckka.w, mul_s(cvB, ck.w));
;             b0 = fma_s(b0, cw.x, t0); b1 = fma_s(b1, cw.y, t1); b2 = fma_s(b2, cw.z, t2); b3 = fma_s(b3, cw.w, t3); }
;           sakA = sel_eq(sakA, psA, jl, q); sakB = sel_eq(sakB, psB, jl, q);
;         }
;     ...
;         SA[(c & 1) * 256 + jl * 16 + row8] = sakA; SA[(c & 1) * 256 + jl * 16 + 8 + row8] = sakB;
;       }
;     } else {
;       if (c >= 1) {
;         const float* d = buf + bprev * CH + jl * 4;
;         const float* dvp = buf + bprev * CH + 320 + row8;
;         const float* dcp = buf + bprev * CH + 336;
;         const float* sap = SA + ((c - 1) & 1) * 256 + row8;
;         f32x4 nw, nkka, nk, nwr; float nvA, nvB, nsA, nsB; f32x2 ncc;
;     ...
;         Y_LOAD(0)
;         float ykA = 0.f, ykB = 0.f;
; #pragma unroll
;         for (int q = 0; q < 16; q++) {
;           const f32x4 cw = nw, ckka = nkka, ck = nk, cwr = nwr; const float cvA = nvA, cvB = nvB, psA = nsA, psB = nsB; const f32x2 ccc = ncc;
;           if (q < 15) Y_LOAD(q + 1)
;           __builtin_amdgcn_sched_barrier(0);
;           float nA0 = mul_s(a0, cwr.x), nA1 = mul_s(a2, cwr.z), nB0 = mul_s(b0, cwr.x), nB1 = mul_s(b2, cwr.z);
.Lsc_loop:
	global_load_dwordx4 v[20:23], v12, s[24:25]
	global_load_dwordx2 v[24:25], v13, s[26:27]
	global_load_dwordx2 v[26:27], v13, s[26:27] offset:128
	global_load_dwordx2 v[28:29], v13, s[26:27] offset:256
	global_load_dwordx2 v[30:31], v13, s[26:27] offset:384
	global_load_ushort v32, v14, s[26:27]
	global_load_dwordx2 v[34:35], v15, s[28:29]
	ds_read_b128 v[44:47], v0 offset:256
	ds_read_b128 v[48:51], v0 offset:512
	ds_read_b128 v[56:59], v0 offset:1024
	ds_read_b128 v[40:43], v0 offset:0
	ds_read_b128 v[52:55], v0 offset:768
	ds_read_b128 v[80:83], v1 offset:0
	ds_read_b128 v[64:67], v0 offset:1536
	ds_read_b128 v[68:71], v0 offset:1792
	ds_read_b128 v[76:79], v0 offset:2304
	ds_read_b128 v[60:63], v0 offset:1280
	ds_read_b128 v[72:75], v0 offset:2048
	s_waitcnt lgkmcnt(9)
	v_mul_f32_e32 v88, v4, v44
	v_mul_f32_e32 v89, v6, v48
	v_fma_f32 v88, v5, v46, v88
	v_fma_f32 v89, v7, v50, v89
	v_mul_f32_e32 v90, v4, v45
	v_add_f32_e32 v92, v88, v89
	v_mul_f32_e32 v91, v6, v49
	v_fma_f32 v90, v5, v47, v90
	v_add_f32_dpp v93, v92, v92 quad_perm:[1,0,3,2] row_mask:0xf bank_mask:0xf
	v_fma_f32 v91, v7, v51, v91
	s_waitcnt lgkmcnt(5)
	v_mul_f32_e32 v96, v80, v56
	v_add_f32_dpp v92, v93, v93 quad_perm:[2,3,0,1] row_mask:0xf bank_mask:0xf
	v_mul_f32_e32 v97, v80, v57
	v_mul_f32_e32 v98, v80, v58
	v_add_f32_dpp v93, v92, v92 row_ror:4 row_mask:0xf bank_mask:0xf
	v_mul_f32_e32 v99, v80, v59
	v_fma_f32 v96, v4, v40, v96
	v_fma_f32 v97, v5, v41, v97
	v_add_f32_dpp v94, v93, v93 row_ror:8 row_mask:0xf bank_mask:0xf
	v_add_f32_dpp v108, v93, v93 row_ror:8 row_mask:0xf bank_mask:0x1
	v_fma_f32 v98, v6, v42, v98
	v_fma_f32 v99, v7, v43, v99
	v_add_f32_e32 v100, v90, v91
	v_fma_f32 v4, -v94, v52, v96
	v_fma_f32 v5, -v94, v53, v97
	v_fma_f32 v6, -v94, v54, v98
	v_fma_f32 v7, -v94, v55, v99
	ds_read_b128 v[44:47], v0 offset:2816
	ds_read_b128 v[48:51], v0 offset:3072
	ds_read_b128 v[56:59], v0 offset:3584
	ds_read_b128 v[40:43], v0 offset:2560
	ds_read_b128 v[52:55], v0 offset:3328
	s_waitcnt lgkmcnt(8)
	v_mul_f32_e32 v88, v4, v64
	v_mul_f32_e32 v89, v6, v68
	v_fma_f32 v88, v5, v66, v88
	v_fma_f32 v89, v7, v70, v89
	v_mul_f32_e32 v90, v4, v65
	v_add_f32_e32 v92, v88, v89
	v_mul_f32_e32 v91, v6, v69
	v_fma_f32 v90, v5, v67, v90
	v_add_f32_dpp v93, v92, v92 quad_perm:[1,0,3,2] row_mask:0xf bank_mask:0xf
	v_fma_f32 v91, v7, v71, v91
	s_waitcnt lgkmcnt(7)
	v_mul_f32_e32 v96, v81, v76
	v_add_f32_dpp v92, v93, v93 quad_perm:[2,3,0,1] row_mask:0xf bank_mask:0xf
	v_mul_f32_e32 v97, v81, v77
	v_mul_f32_e32 v98, v81, v78
	v_add_f32_dpp v93, v92, v92 row_ror:4 row_mask:0xf bank_mask:0xf
	v_mul_f32_e32 v99, v81, v79
	s_waitcnt lgkmcnt(6)
	v_fma_f32 v96, v4, v60, v96
	v_fma_f32 v97, v5, v61, v97
	v_add_f32_dpp v94, v93, v93 row_ror:8 row_mask:0xf bank_mask:0xf
	v_add_f32_dpp v108, v93, v93 row_ror:8 row_mask:0xf bank_mask:0x4
	v_fma_f32 v98, v6, v62, v98
	v_fma_f32 v99, v7, v63, v99
	v_add_f32_e32 v101, v90, v91
	s_waitcnt lgkmcnt(5)
	v_fma_f32 v4, -v94, v72, v96
	v_fma_f32 v5, -v94, v73, v97
	v_fma_f32 v6, -v94, v74, v98
	v_fma_f32 v7, -v94, v75, v99
	v_add_f32_dpp v100, v100, v100 row_ror:8 row_mask:0xf bank_mask:0x3
	s_nop 1
	v_add_f32_dpp v100, v101, v101 row_ror:8 row_mask:0xf bank_mask:0xc
	ds_read_b128 v[64:67], v0 offset:4096
	ds_read_b128 v[68:71], v0 offset:4352
	ds_read_b128 v[76:79], v0 offset:4864
	ds_read_b128 v[60:63], v0 offset:3840
	ds_read_b128 v[72:75], v0 offset:4608
	s_waitcnt lgkmcnt(8)
	v_mul_f32_e32 v88, v4, v44
	v_mul_f32_e32 v89, v6, v48
	v_fma_f32 v88, v5, v46, v88
	v_fma_f32 v89, v7, v50, v89
	v_mul_f32_e32 v90, v4, v45
	v_add_f32_e32 v92, v88, v89
	v_mul_f32_e32 v91, v6, v49
	v_fma_f32 v90, v5, v47, v90
	v_add_f32_dpp v93, v92, v92 quad_perm:[1,0,3,2] row_mask:0xf bank_mask:0xf
	v_fma_f32 v91, v7, v51, v91
	s_waitcnt lgkmcnt(7)
	v_mul_f32_e32 v96, v82, v56
	v_add_f32_dpp v92, v93, v93 quad_perm:[2,3,0,1] row_mask:0xf bank_mask:0xf
	v_mul_f32_e32 v97, v82, v57
	v_mul_f32_e32 v98, v82, v58
	v_add_f32_dpp v93, v92, v92 row_ror:4 row_mask:0xf bank_mask:0xf
	v_mul_f32_e32 v99, v82, v59
	s_waitcnt lgkmcnt(6)
	v_fma_f32 v96, v4, v40, v96
	v_fma_f32 v97, v5, v41, v97
	v_add_f32_dpp v94, v93, v93 row_ror:8 row_mask:0xf bank_mask:0xf
	v_add_f32_dpp v108, v93, v93 row_ror:8 row_mask:0xf bank_mask:0x2
	v_fma_f32 v98, v6, v42, v98
	v_fma_f32 v99, v7, v43, v99
	v_add_f32_e32 v102, v90, v91
	s_waitcnt lgkmcnt(5)
	v_fma_f32 v4, -v94, v52, v96
	v_fma_f32 v5, -v94, v53, v97
	v_fma_f32 v6, -v94, v54, v98
	v_fma_f32 v7, -v94, v55, v99
	ds_read_b128 v[44:47], v0 offset:5376
	ds_read_b128 v[48:51], v0 offset:5632
	ds_read_b128 v[56:59], v0 offset:6144
	ds_read_b128 v[40:43], v0 offset:5120
	ds_read_b128 v[52:55], v0 offset:5888
	ds_read_b128 v[84:87], v1 offset:16
	s_waitcnt lgkmcnt(9)
	v_mul_f32_e32 v88, v4, v64
	v_mul_f32_e32 v89, v6, v68
	v_fma_f32 v88, v5, v66, v88
	v_fma_f32 v89, v7, v70, v89
	v_mul_f32_e32 v90, v4, v65
	v_add_f32_e32 v92, v88, v89
	v_mul_f32_e32 v91, v6, v69
	v_fma_f32 v90, v5, v67, v90
	v_add_f32_dpp v93, v92, v92 quad_perm:[1,0,3,2] row_mask:0xf bank_mask:0xf
	v_fma_f32 v91, v7, v71, v91
	s_waitcnt lgkmcnt(8)
	v_mul_f32_e32 v96, v83, v76
	v_add_f32_dpp v92, v93, v93 quad_perm:[2,3,0,1] row_mask:0xf bank_mask:0xf
	v_mul_f32_e32 v97, v83, v77
	v_mul_f32_e32 v98, v83, v78
	v_add_f32_dpp v93, v92, v92 row_ror:4 row_mask:0xf bank_mask:0xf
	v_mul_f32_e32 v99, v83, v79
	s_waitcnt lgkmcnt(7)
	v_fma_f32 v96, v4, v60, v96
	v_fma_f32 v97, v5, v61, v97
	v_add_f32_dpp v94, v93, v93 row_ror:8 row_mask:0xf bank_mask:0xf
	v_add_f32_dpp v108, v93, v93 row_ror:8 row_mask:0xf bank_mask:0x8
	v_fma_f32 v98, v6, v62, v98
	v_fma_f32 v99, v7, v63, v99
	v_add_f32_e32 v103, v90, v91
	s_waitcnt lgkmcnt(6)
; __device__ __forceinline__ void rwkv_scan2_item(const Params& p, int item, char* ldsraw) {
;     ...
;         for (int q = 0; q < 16; q++) {
;           const f32x4 cw = nw, ckk = nkk, ckka = nkka, ck = nk; const float cvA = nvA, cvB = nvB;
;           if (q < 15) R_LOAD(q + 1)
;           __builtin_amdgcn_sched_barrier(0);
;           float mA0 = mul_s(a0, ckk.x), mA1 = mul_s(a2, ckk.z), mB0 = mul_s(b0, ckk.x), mB1 = mul_s(b2, ckk.z);
;           mA0 = fma_s(a1, ckk.y, mA0); mA1 = fma_s(a3, ckk.w, mA1); mB0 = fma_s(b1, ckk.y, mB0); mB1 = fma_s(b3, ckk.w, mB1);
;           float psA = add_s(mA0, mA1), psB = add_s(mB0, mB1);
;           psA = row16_sum(psA); psB = row16_sum(psB);
;           { const float t0 = fnma_s(psA, ckka.x, mul_s(cvA, ck.x)), t1 = fnma_s(psA, ckka.y, mul_s(cvA, ck.y));
;             const float t2 = fnma_s(psA, ckka.z, mul_s(cvA, ck.z)), t3 = fnma_s(psA, ckka.w, mul_s(cvA, ck.w));
;             a0 = fma_s(a0, cw.x, t0); a1 = fma_s(a1, cw.y, t1); a2 = fma_s(a2, cw.z, t2); a3 = fma_s(a3, cw.w, t3); }
;           { const float t0 = fnma_s(psB, ckka.x, mul_s(cvB, ck.x)), t1 = fnma_s(psB, ckka.y, mul_s(cvB, ck.y));
;             const float t2 = fnma_s(psB, ckka.z, mul_s(cvB, ck.z)), t3 = fnma_s(psB, ckka.w, mul_s(cvB, ck.w));
;             b0 = fma_s(b0, cw.x, t0); b1 = fma_s(b1, cw.y, t1); b2 = fma_s(b2, cw.z, t2); b3 = fma_s(b3, cw.w, t3); }
;           sakA = sel_eq(sakA, psA, jl, q); sakB = sel_eq(sakB, psB, jl, q);
;         }
;     ...
;         SA[(c & 1) * 256 + jl * 16 + row8] = sakA; SA[(c & 1) * 256 + jl * 16 + 8 + row8] = sakB;
;       }
;     } else {
;       if (c >= 1) {
;         const float* d = buf + bprev * CH + jl * 4;
;         const float* dvp = buf + bprev * CH + 320 + row8;
;         const float* dcp = buf + bprev * CH + 336;
;         const float* sap = SA + ((c - 1) & 1) * 256 + row8;
;         f32x4 nw, nkka, nk, nwr; float nvA, nvB, nsA, nsB; f32x2 ncc;
;     ...
;         Y_LOAD(0)
;         float ykA = 0.f, ykB = 0.f;
; #pragma unroll
;         for (int q = 0; q < 16; q++) {
;           const f32x4 cw = nw, ckka = nkka, ck = nk, cwr = nwr; const float cvA = nvA, cvB = nvB, psA = nsA, psB = nsB; const f32x2 ccc = ncc;
;           if (q < 15) Y_LOAD(q + 1)
;           __builtin_amdgcn_sched_barrier(0);
;           float nA0 = mul_s(a0, cwr.x), nA1 = mul_s(a2, cwr.z), nB0 = mul_s(b0, cwr.x), nB1 = mul_s(b2, cwr.z);
	v_fma_f32 v4, -v94, v72, v96
	v_fma_f32 v5, -v94, v73, v97
	v_fma_f32 v6, -v94, v74, v98
	v_fma_f32 v7, -v94, v75, v99
	v_add_f32_dpp v102, v102, v102 row_ror:8 row_mask:0xf bank_mask:0x3
	s_nop 1
	v_add_f32_dpp v102, v103, v103 row_ror:8 row_mask:0xf bank_mask:0xc
	v_add_f32_dpp v100, v100, v100 row_half_mirror row_mask:0xf bank_mask:0x5
	s_nop 1
	v_add_f32_dpp v100, v102, v102 row_half_mirror row_mask:0xf bank_mask:0xa
	ds_read_b128 v[64:67], v0 offset:6656
	ds_read_b128 v[68:71], v0 offset:6912
	ds_read_b128 v[76:79], v0 offset:7424
	ds_read_b128 v[60:63], v0 offset:6400
	ds_read_b128 v[72:75], v0 offset:7168
	s_waitcnt lgkmcnt(9)
	v_mul_f32_e32 v88, v4, v44
	v_mul_f32_e32 v89, v6, v48
	v_fma_f32 v88, v5, v46, v88
	v_fma_f32 v89, v7, v50, v89
	v_mul_f32_e32 v90, v4, v45
	v_add_f32_e32 v92, v88, v89
	v_mul_f32_e32 v91, v6, v49
	v_fma_f32 v90, v5, v47, v90
	v_add_f32_dpp v93, v92, v92 quad_perm:[1,0,3,2] row_mask:0xf bank_mask:0xf
	v_fma_f32 v91, v7, v51, v91
	s_waitcnt lgkmcnt(5)
	v_mul_f32_e32 v96, v84, v56
	v_add_f32_dpp v92, v93, v93 quad_perm:[2,3,0,1] row_mask:0xf bank_mask:0xf
	v_mul_f32_e32 v97, v84, v57
	v_mul_f32_e32 v98, v84, v58
	v_add_f32_dpp v93, v92, v92 row_ror:4 row_mask:0xf bank_mask:0xf
	v_mul_f32_e32 v99, v84, v59
	v_fma_f32 v96, v4, v40, v96
	v_fma_f32 v97, v5, v41, v97
	v_add_f32_dpp v94, v93, v93 row_ror:8 row_mask:0xf bank_mask:0xf
	v_add_f32_dpp v109, v93, v93 row_ror:8 row_mask:0xf bank_mask:0x1
	v_fma_f32 v98, v6, v42, v98
	v_fma_f32 v99, v7, v43, v99
	v_add_f32_e32 v104, v90, v91
	v_fma_f32 v4, -v94, v52, v96
	v_fma_f32 v5, -v94, v53, v97
	v_fma_f32 v6, -v94, v54, v98
	v_fma_f32 v7, -v94, v55, v99
	ds_read_b128 v[44:47], v0 offset:7936
	ds_read_b128 v[48:51], v0 offset:8192
	ds_read_b128 v[56:59], v0 offset:8704
	ds_read_b128 v[40:43], v0 offset:7680
	ds_read_b128 v[52:55], v0 offset:8448
	s_waitcnt lgkmcnt(8)
	v_mul_f32_e32 v88, v4, v64
	v_mul_f32_e32 v89, v6, v68
	v_fma_f32 v88, v5, v66, v88
	v_fma_f32 v89, v7, v70, v89
	v_mul_f32_e32 v90, v4, v65
	v_add_f32_e32 v92, v88, v89
	v_mul_f32_e32 v91, v6, v69
	v_fma_f32 v90, v5, v67, v90
	v_add_f32_dpp v93, v92, v92 quad_perm:[1,0,3,2] row_mask:0xf bank_mask:0xf
	v_fma_f32 v91, v7, v71, v91
	s_waitcnt lgkmcnt(7)
	v_mul_f32_e32 v96, v85, v76
	v_add_f32_dpp v92, v93, v93 quad_perm:[2,3,0,1] row_mask:0xf bank_mask:0xf
	v_mul_f32_e32 v97, v85, v77
	v_mul_f32_e32 v98, v85, v78
	v_add_f32_dpp v93, v92, v92 row_ror:4 row_mask:0xf bank_mask:0xf
	v_mul_f32_e32 v99, v85, v79
	s_waitcnt lgkmcnt(6)
	v_fma_f32 v96, v4, v60, v96
	v_fma_f32 v97, v5, v61, v97
	v_add_f32_dpp v94, v93, v93 row_ror:8 row_mask:0xf bank_mask:0xf
	v_add_f32_dpp v109, v93, v93 row_ror:8 row_mask:0xf bank_mask:0x4
	v_fma_f32 v98, v6, v62, v98
	v_fma_f32 v99, v7, v63, v99
	v_add_f32_e32 v105, v90, v91
	s_waitcnt lgkmcnt(5)
	v_fma_f32 v4, -v94, v72, v96
	v_fma_f32 v5, -v94, v73, v97
	v_fma_f32 v6, -v94, v74, v98
	v_fma_f32 v7, -v94, v75, v99
	v_add_f32_dpp v104, v104, v104 row_ror:8 row_mask:0xf bank_mask:0x3
	s_nop 1
	v_add_f32_dpp v104, v105, v105 row_ror:8 row_mask:0xf bank_mask:0xc
	ds_read_b128 v[64:67], v0 offset:9216
	ds_read_b128 v[68:71], v0 offset:9472
	ds_read_b128 v[76:79], v0 offset:9984
	ds_read_b128 v[60:63], v0 offset:8960
	ds_read_b128 v[72:75], v0 offset:9728
	s_waitcnt lgkmcnt(8)
	v_mul_f32_e32 v88, v4, v44
	v_mul_f32_e32 v89, v6, v48
	v_fma_f32 v88, v5, v46, v88
	v_fma_f32 v89, v7, v50, v89
	v_mul_f32_e32 v90, v4, v45
	v_add_f32_e32 v92, v88, v89
	v_mul_f32_e32 v91, v6, v49
	v_fma_f32 v90, v5, v47, v90
	v_add_f32_dpp v93, v92, v92 quad_perm:[1,0,3,2] row_mask:0xf bank_mask:0xf
	v_fma_f32 v91, v7, v51, v91
	s_waitcnt lgkmcnt(7)
	v_mul_f32_e32 v96, v86, v56
	v_add_f32_dpp v92, v93, v93 quad_perm:[2,3,0,1] row_mask:0xf bank_mask:0xf
	v_mul_f32_e32 v97, v86, v57
	v_mul_f32_e32 v98, v86, v58
	v_add_f32_dpp v93, v92, v92 row_ror:4 row_mask:0xf bank_mask:0xf
	v_mul_f32_e32 v99, v86, v59
	s_waitcnt lgkmcnt(6)
	v_fma_f32 v96, v4, v40, v96
	v_fma_f32 v97, v5, v41, v97
	v_add_f32_dpp v94, v93, v93 row_ror:8 row_mask:0xf bank_mask:0xf
	v_add_f32_dpp v109, v93, v93 row_ror:8 row_mask:0xf bank_mask:0x2
	v_fma_f32 v98, v6, v42, v98
	v_fma_f32 v99, v7, v43, v99
	v_add_f32_e32 v101, v90, v91
	s_waitcnt lgkmcnt(5)
	v_fma_f32 v4, -v94, v52, v96
	v_fma_f32 v5, -v94, v53, v97
	v_fma_f32 v6, -v94, v54, v98
	v_fma_f32 v7, -v94, v55, v99
	ds_read_b128 v[44:47], v0 offset:10496
	ds_read_b128 v[48:51], v0 offset:10752
	ds_read_b128 v[56:59], v0 offset:11264
	ds_read_b128 v[40:43], v0 offset:10240
	ds_read_b128 v[52:55], v0 offset:11008
	ds_read_b128 v[80:83], v1 offset:32
	s_waitcnt lgkmcnt(9)
	v_mul_f32_e32 v88, v4, v64
	v_mul_f32_e32 v89, v6, v68
	v_fma_f32 v88, v5, v66, v88
	v_fma_f32 v89, v7, v70, v89
	v_mul_f32_e32 v90, v4, v65
	v_add_f32_e32 v92, v88, v89
	v_mul_f32_e32 v91, v6, v69
	v_fma_f32 v90, v5, v67, v90
	v_add_f32_dpp v93, v92, v92 quad_perm:[1,0,3,2] row_mask:0xf bank_mask:0xf
	v_fma_f32 v91, v7, v71, v91
	s_waitcnt lgkmcnt(8)
	v_mul_f32_e32 v96, v87, v76
	v_add_f32_dpp v92, v93, v93 quad_perm:[2,3,0,1] row_mask:0xf bank_mask:0xf
	v_mul_f32_e32 v97, v87, v77
	v_mul_f32_e32 v98, v87, v78
	v_add_f32_dpp v93, v92, v92 row_ror:4 row_mask:0xf bank_mask:0xf
	v_mul_f32_e32 v99, v87, v79
	s_waitcnt lgkmcnt(7)
	v_fma_f32 v96, v4, v60, v96
	v_fma_f32 v97, v5, v61, v97
	v_add_f32_dpp v94, v93, v93 row_ror:8 row_mask:0xf bank_mask:0xf
	v_add_f32_dpp v109, v93, v93 row_ror:8 row_mask:0xf bank_mask:0x8
	v_fma_f32 v98, v6, v62, v98
	v_fma_f32 v99, v7, v63, v99
	v_add_f32_e32 v103, v90, v91
	s_waitcnt lgkmcnt(6)
; __device__ __forceinline__ void rwkv_scan2_item(const Params& p, int item, char* ldsraw) {
;     ...
;         for (int q = 0; q < 16; q++) {
;           const f32x4 cw = nw, ckk = nkk, ckka = nkka, ck = nk; const float cvA = nvA, cvB = nvB;
;           if (q < 15) R_LOAD(q + 1)
;           __builtin_amdgcn_sched_barrier(0);
;           float mA0 = mul_s(a0, ckk.x), mA1 = mul_s(a2, ckk.z), mB0 = mul_s(b0, ckk.x), mB1 = mul_s(b2, ckk.z);
;           mA0 = fma_s(a1, ckk.y, mA0); mA1 = fma_s(a3, ckk.w, mA1); mB0 = fma_s(b1, ckk.y, mB0); mB1 = fma_s(b3, ckk.w, mB1);
;           float psA = add_s(mA0, mA1), psB = add_s(mB0, mB1);
;           psA = row16_sum(psA); psB = row16_sum(psB);
;           { const float t0 = fnma_s(psA, ckka.x, mul_s(cvA, ck.x)), t1 = fnma_s(psA, ckka.y, mul_s(cvA, ck.y));
;             const float t2 = fnma_s(psA, ckka.z, mul_s(cvA, ck.z)), t3 = fnma_s(psA, ckka.w, mul_s(cvA, ck.w));
;             a0 = fma_s(a0, cw.x, t0); a1 = fma_s(a1, cw.y, t1); a2 = fma_s(a2, cw.z, t2); a3 = fma_s(a3, cw.w, t3); }
;           { const float t0 = fnma_s(psB, ckka.x, mul_s(cvB, ck.x)), t1 = fnma_s(psB, ckka.y, mul_s(cvB, ck.y));
;             const float t2 = fnma_s(psB, ckka.z, mul_s(cvB, ck.z)), t3 = fnma_s(psB, ckka.w, mul_s(cvB, ck.w));
;             b0 = fma_s(b0, cw.x, t0); b1 = fma_s(b1, cw.y, t1); b2 = fma_s(b2, cw.z, t2); b3 = fma_s(b3, cw.w, t3); }
;           sakA = sel_eq(sakA, psA, jl, q); sakB = sel_eq(sakB, psB, jl, q);
;         }
;     ...
;         SA[(c & 1) * 256 + jl * 16 + row8] = sakA; SA[(c & 1) * 256 + jl * 16 + 8 + row8] = sakB;
;       }
;     } else {
;       if (c >= 1) {
;         const float* d = buf + bprev * CH + jl * 4;
;         const float* dvp = buf + bprev * CH + 320 + row8;
;         const float* dcp = buf + bprev * CH + 336;
;         const float* sap = SA + ((c - 1) & 1) * 256 + row8;
;         f32x4 nw, nkka, nk, nwr; float nvA, nvB, nsA, nsB; f32x2 ncc;
;     ...
;         Y_LOAD(0)
;         float ykA = 0.f, ykB = 0.f;
; #pragma unroll
;         for (int q = 0; q < 16; q++) {
;           const f32x4 cw = nw, ckka = nkka, ck = nk, cwr = nwr; const float cvA = nvA, cvB = nvB, psA = nsA, psB = nsB; const f32x2 ccc = ncc;
;           if (q < 15) Y_LOAD(q + 1)
;           __builtin_amdgcn_sched_barrier(0);
;           float nA0 = mul_s(a0, cwr.x), nA1 = mul_s(a2, cwr.z), nB0 = mul_s(b0, cwr.x), nB1 = mul_s(b2, cwr.z);
	v_fma_f32 v4, -v94, v72, v96
	v_fma_f32 v5, -v94, v73, v97
	v_fma_f32 v6, -v94, v74, v98
	v_fma_f32 v7, -v94, v75, v99
	v_add_f32_dpp v101, v101, v101 row_ror:8 row_mask:0xf bank_mask:0x3
	s_nop 1
	v_add_f32_dpp v101, v103, v103 row_ror:8 row_mask:0xf bank_mask:0xc
	v_add_f32_dpp v104, v104, v104 row_half_mirror row_mask:0xf bank_mask:0x5
	s_nop 1
	v_add_f32_dpp v104, v101, v101 row_half_mirror row_mask:0xf bank_mask:0xa
	v_cndmask_b32_e64 v106, v104, v100, s[36:37]
	v_cndmask_b32_e64 v107, v100, v104, s[36:37]
	s_nop 1
	v_add_f32_dpp v100, v106, v107 quad_perm:[2,3,0,1] row_mask:0xf bank_mask:0xf
	ds_read_b128 v[64:67], v0 offset:11776
	ds_read_b128 v[68:71], v0 offset:12032
	ds_read_b128 v[76:79], v0 offset:12544
	ds_read_b128 v[60:63], v0 offset:11520
	ds_read_b128 v[72:75], v0 offset:12288
	s_waitcnt lgkmcnt(9)
	v_mul_f32_e32 v88, v4, v44
	v_mul_f32_e32 v89, v6, v48
	v_fma_f32 v88, v5, v46, v88
	v_fma_f32 v89, v7, v50, v89
	v_mul_f32_e32 v90, v4, v45
	v_add_f32_e32 v92, v88, v89
	v_mul_f32_e32 v91, v6, v49
	v_fma_f32 v90, v5, v47, v90
	v_add_f32_dpp v93, v92, v92 quad_perm:[1,0,3,2] row_mask:0xf bank_mask:0xf
	v_fma_f32 v91, v7, v51, v91
	s_waitcnt lgkmcnt(5)
	v_mul_f32_e32 v96, v80, v56
	v_add_f32_dpp v92, v93, v93 quad_perm:[2,3,0,1] row_mask:0xf bank_mask:0xf
	v_mul_f32_e32 v97, v80, v57
	v_mul_f32_e32 v98, v80, v58
	v_add_f32_dpp v93, v92, v92 row_ror:4 row_mask:0xf bank_mask:0xf
	v_mul_f32_e32 v99, v80, v59
	v_fma_f32 v96, v4, v40, v96
	v_fma_f32 v97, v5, v41, v97
	v_add_f32_dpp v94, v93, v93 row_ror:8 row_mask:0xf bank_mask:0xf
	v_add_f32_dpp v110, v93, v93 row_ror:8 row_mask:0xf bank_mask:0x1
	v_fma_f32 v98, v6, v42, v98
	v_fma_f32 v99, v7, v43, v99
	v_add_f32_e32 v102, v90, v91
	v_fma_f32 v4, -v94, v52, v96
	v_fma_f32 v5, -v94, v53, v97
	v_fma_f32 v6, -v94, v54, v98
	v_fma_f32 v7, -v94, v55, v99
	ds_read_b128 v[44:47], v0 offset:13056
	ds_read_b128 v[48:51], v0 offset:13312
	ds_read_b128 v[56:59], v0 offset:13824
	ds_read_b128 v[40:43], v0 offset:12800
	ds_read_b128 v[52:55], v0 offset:13568
	s_waitcnt lgkmcnt(8)
	v_mul_f32_e32 v88, v4, v64
	v_mul_f32_e32 v89, v6, v68
	v_fma_f32 v88, v5, v66, v88
	v_fma_f32 v89, v7, v70, v89
	v_mul_f32_e32 v90, v4, v65
	v_add_f32_e32 v92, v88, v89
	v_mul_f32_e32 v91, v6, v69
	v_fma_f32 v90, v5, v67, v90
	v_add_f32_dpp v93, v92, v92 quad_perm:[1,0,3,2] row_mask:0xf bank_mask:0xf
	v_fma_f32 v91, v7, v71, v91
	s_waitcnt lgkmcnt(7)
	v_mul_f32_e32 v96, v81, v76
	v_add_f32_dpp v92, v93, v93 quad_perm:[2,3,0,1] row_mask:0xf bank_mask:0xf
	v_mul_f32_e32 v97, v81, v77
	v_mul_f32_e32 v98, v81, v78
	v_add_f32_dpp v93, v92, v92 row_ror:4 row_mask:0xf bank_mask:0xf
	v_mul_f32_e32 v99, v81, v79
	s_waitcnt lgkmcnt(6)
	v_fma_f32 v96, v4, v60, v96
	v_fma_f32 v97, v5, v61, v97
	v_add_f32_dpp v94, v93, v93 row_ror:8 row_mask:0xf bank_mask:0xf
	v_add_f32_dpp v110, v93, v93 row_ror:8 row_mask:0xf bank_mask:0x4
	v_fma_f32 v98, v6, v62, v98
	v_fma_f32 v99, v7, v63, v99
	v_add_f32_e32 v105, v90, v91
	s_waitcnt lgkmcnt(5)
	v_fma_f32 v4, -v94, v72, v96
	v_fma_f32 v5, -v94, v73, v97
	v_fma_f32 v6, -v94, v74, v98
	v_fma_f32 v7, -v94, v75, v99
	v_add_f32_dpp v102, v102, v102 row_ror:8 row_mask:0xf bank_mask:0x3
	s_nop 1
	v_add_f32_dpp v102, v105, v105 row_ror:8 row_mask:0xf bank_mask:0xc
	ds_read_b128 v[64:67], v0 offset:14336
	ds_read_b128 v[68:71], v0 offset:14592
	ds_read_b128 v[76:79], v0 offset:15104
	ds_read_b128 v[60:63], v0 offset:14080
	ds_read_b128 v[72:75], v0 offset:14848
	s_waitcnt lgkmcnt(8)
	v_mul_f32_e32 v88, v4, v44
	v_mul_f32_e32 v89, v6, v48
	v_fma_f32 v88, v5, v46, v88
	v_fma_f32 v89, v7, v50, v89
	v_mul_f32_e32 v90, v4, v45
	v_add_f32_e32 v92, v88, v89
	v_mul_f32_e32 v91, v6, v49
	v_fma_f32 v90, v5, v47, v90
	v_add_f32_dpp v93, v92, v92 quad_perm:[1,0,3,2] row_mask:0xf bank_mask:0xf
	v_fma_f32 v91, v7, v51, v91
	s_waitcnt lgkmcnt(7)
	v_mul_f32_e32 v96, v82, v56
	v_add_f32_dpp v92, v93, v93 quad_perm:[2,3,0,1] row_mask:0xf bank_mask:0xf
	v_mul_f32_e32 v97, v82, v57
	v_mul_f32_e32 v98, v82, v58
	v_add_f32_dpp v93, v92, v92 row_ror:4 row_mask:0xf bank_mask:0xf
	v_mul_f32_e32 v99, v82, v59
	s_waitcnt lgkmcnt(6)
	v_fma_f32 v96, v4, v40, v96
	v_fma_f32 v97, v5, v41, v97
	v_add_f32_dpp v94, v93, v93 row_ror:8 row_mask:0xf bank_mask:0xf
	v_add_f32_dpp v110, v93, v93 row_ror:8 row_mask:0xf bank_mask:0x2
	v_fma_f32 v98, v6, v42, v98
	v_fma_f32 v99, v7, v43, v99
	v_add_f32_e32 v103, v90, v91
	s_waitcnt lgkmcnt(5)
	v_fma_f32 v4, -v94, v52, v96
	v_fma_f32 v5, -v94, v53, v97
	v_fma_f32 v6, -v94, v54, v98
	v_fma_f32 v7, -v94, v55, v99
	ds_read_b128 v[44:47], v0 offset:15616
	ds_read_b128 v[48:51], v0 offset:15872
	ds_read_b128 v[56:59], v0 offset:16384
	ds_read_b128 v[40:43], v0 offset:15360
	ds_read_b128 v[52:55], v0 offset:16128
	ds_read_b128 v[84:87], v1 offset:48
	s_waitcnt lgkmcnt(9)
	v_mul_f32_e32 v88, v4, v64
	v_mul_f32_e32 v89, v6, v68
	v_fma_f32 v88, v5, v66, v88
	v_fma_f32 v89, v7, v70, v89
	v_mul_f32_e32 v90, v4, v65
	v_add_f32_e32 v92, v88, v89
	v_mul_f32_e32 v91, v6, v69
	v_fma_f32 v90, v5, v67, v90
	v_add_f32_dpp v93, v92, v92 quad_perm:[1,0,3,2] row_mask:0xf bank_mask:0xf
	v_fma_f32 v91, v7, v71, v91
	s_waitcnt lgkmcnt(8)
	v_mul_f32_e32 v96, v83, v76
	v_add_f32_dpp v92, v93, v93 quad_perm:[2,3,0,1] row_mask:0xf bank_mask:0xf
	v_mul_f32_e32 v97, v83, v77
	v_mul_f32_e32 v98, v83, v78
	v_add_f32_dpp v93, v92, v92 row_ror:4 row_mask:0xf bank_mask:0xf
	v_mul_f32_e32 v99, v83, v79
	s_waitcnt lgkmcnt(7)
	v_fma_f32 v96, v4, v60, v96
	v_fma_f32 v97, v5, v61, v97
	v_add_f32_dpp v94, v93, v93 row_ror:8 row_mask:0xf bank_mask:0xf
	v_add_f32_dpp v110, v93, v93 row_ror:8 row_mask:0xf bank_mask:0x8
	v_fma_f32 v98, v6, v62, v98
	v_fma_f32 v99, v7, v63, v99
	v_add_f32_e32 v101, v90, v91
	s_waitcnt lgkmcnt(6)
; __device__ __forceinline__ void rwkv_scan2_item(const Params& p, int item, char* ldsraw) {
;     ...
;         for (int q = 0; q < 16; q++) {
;           const f32x4 cw = nw, ckk = nkk, ckka = nkka, ck = nk; const float cvA = nvA, cvB = nvB;
;           if (q < 15) R_LOAD(q + 1)
;           __builtin_amdgcn_sched_barrier(0);
;           float mA0 = mul_s(a0, ckk.x), mA1 = mul_s(a2, ckk.z), mB0 = mul_s(b0, ckk.x), mB1 = mul_s(b2, ckk.z);
;           mA0 = fma_s(a1, ckk.y, mA0); mA1 = fma_s(a3, ckk.w, mA1); mB0 = fma_s(b1, ckk.y, mB0); mB1 = fma_s(b3, ckk.w, mB1);
;           float psA = add_s(mA0, mA1), psB = add_s(mB0, mB1);
;           psA = row16_sum(psA); psB = row16_sum(psB);
;           { const float t0 = fnma_s(psA, ckka.x, mul_s(cvA, ck.x)), t1 = fnma_s(psA, ckka.y, mul_s(cvA, ck.y));
;             const float t2 = fnma_s(psA, ckka.z, mul_s(cvA, ck.z)), t3 = fnma_s(psA, ckka.w, mul_s(cvA, ck.w));
;             a0 = fma_s(a0, cw.x, t0); a1 = fma_s(a1, cw.y, t1); a2 = fma_s(a2, cw.z, t2); a3 = fma_s(a3, cw.w, t3); }
;           { const float t0 = fnma_s(psB, ckka.x, mul_s(cvB, ck.x)), t1 = fnma_s(psB, ckka.y, mul_s(cvB, ck.y));
;             const float t2 = fnma_s(psB, ckka.z, mul_s(cvB, ck.z)), t3 = fnma_s(psB, ckka.w, mul_s(cvB, ck.w));
;             b0 = fma_s(b0, cw.x, t0); b1 = fma_s(b1, cw.y, t1); b2 = fma_s(b2, cw.z, t2); b3 = fma_s(b3, cw.w, t3); }
;           sakA = sel_eq(sakA, psA, jl, q); sakB = sel_eq(sakB, psB, jl, q);
;         }
;     ...
;         SA[(c & 1) * 256 + jl * 16 + row8] = sakA; SA[(c & 1) * 256 + jl * 16 + 8 + row8] = sakB;
;       }
;     } else {
;       if (c >= 1) {
;         const float* d = buf + bprev * CH + jl * 4;
;         const float* dvp = buf + bprev * CH + 320 + row8;
;         const float* dcp = buf + bprev * CH + 336;
;         const float* sap = SA + ((c - 1) & 1) * 256 + row8;
;         f32x4 nw, nkka, nk, nwr; float nvA, nvB, nsA, nsB; f32x2 ncc;
;     ...
;         Y_LOAD(0)
;         float ykA = 0.f, ykB = 0.f;
; #pragma unroll
;         for (int q = 0; q < 16; q++) {
;           const f32x4 cw = nw, ckka = nkka, ck = nk, cwr = nwr; const float cvA = nvA, cvB = nvB, psA = nsA, psB = nsB; const f32x2 ccc = ncc;
;           if (q < 15) Y_LOAD(q + 1)
;           __builtin_amdgcn_sched_barrier(0);
;           float nA0 = mul_s(a0, cwr.x), nA1 = mul_s(a2, cwr.z), nB0 = mul_s(b0, cwr.x), nB1 = mul_s(b2, cwr.z);
	v_fma_f32 v4, -v94, v72, v96
	v_fma_f32 v5, -v94, v73, v97
	v_fma_f32 v6, -v94, v74, v98
	v_fma_f32 v7, -v94, v75, v99
	v_add_f32_dpp v103, v103, v103 row_ror:8 row_mask:0xf bank_mask:0x3
	s_nop 1
	v_add_f32_dpp v103, v101, v101 row_ror:8 row_mask:0xf bank_mask:0xc
	v_add_f32_dpp v102, v102, v102 row_half_mirror row_mask:0xf bank_mask:0x5
	s_nop 1
	v_add_f32_dpp v102, v103, v103 row_half_mirror row_mask:0xf bank_mask:0xa
	ds_read_b128 v[64:67], v0 offset:16896
	ds_read_b128 v[68:71], v0 offset:17152
	ds_read_b128 v[76:79], v0 offset:17664
	ds_read_b128 v[60:63], v0 offset:16640
	ds_read_b128 v[72:75], v0 offset:17408
	s_waitcnt lgkmcnt(9)
	v_mul_f32_e32 v88, v4, v44
	v_mul_f32_e32 v89, v6, v48
	v_fma_f32 v88, v5, v46, v88
	v_fma_f32 v89, v7, v50, v89
	v_mul_f32_e32 v90, v4, v45
	v_add_f32_e32 v92, v88, v89
	v_mul_f32_e32 v91, v6, v49
	v_fma_f32 v90, v5, v47, v90
	v_add_f32_dpp v93, v92, v92 quad_perm:[1,0,3,2] row_mask:0xf bank_mask:0xf
	v_fma_f32 v91, v7, v51, v91
	s_waitcnt lgkmcnt(5)
	v_mul_f32_e32 v96, v84, v56
	v_add_f32_dpp v92, v93, v93 quad_perm:[2,3,0,1] row_mask:0xf bank_mask:0xf
	v_mul_f32_e32 v97, v84, v57
	v_mul_f32_e32 v98, v84, v58
	v_add_f32_dpp v93, v92, v92 row_ror:4 row_mask:0xf bank_mask:0xf
	v_mul_f32_e32 v99, v84, v59
	v_fma_f32 v96, v4, v40, v96
	v_fma_f32 v97, v5, v41, v97
	v_add_f32_dpp v94, v93, v93 row_ror:8 row_mask:0xf bank_mask:0xf
	v_add_f32_dpp v111, v93, v93 row_ror:8 row_mask:0xf bank_mask:0x1
	v_fma_f32 v98, v6, v42, v98
	v_fma_f32 v99, v7, v43, v99
	v_add_f32_e32 v104, v90, v91
	v_fma_f32 v4, -v94, v52, v96
	v_fma_f32 v5, -v94, v53, v97
	v_fma_f32 v6, -v94, v54, v98
	v_fma_f32 v7, -v94, v55, v99
	ds_read_b128 v[44:47], v0 offset:18176
	ds_read_b128 v[48:51], v0 offset:18432
	ds_read_b128 v[56:59], v0 offset:18944
	ds_read_b128 v[40:43], v0 offset:17920
	ds_read_b128 v[52:55], v0 offset:18688
	s_waitcnt lgkmcnt(8)
	v_mul_f32_e32 v88, v4, v64
	v_mul_f32_e32 v89, v6, v68
	v_fma_f32 v88, v5, v66, v88
	v_fma_f32 v89, v7, v70, v89
	v_mul_f32_e32 v90, v4, v65
	v_add_f32_e32 v92, v88, v89
	v_mul_f32_e32 v91, v6, v69
	v_fma_f32 v90, v5, v67, v90
	v_add_f32_dpp v93, v92, v92 quad_perm:[1,0,3,2] row_mask:0xf bank_mask:0xf
	v_fma_f32 v91, v7, v71, v91
	s_waitcnt lgkmcnt(7)
	v_mul_f32_e32 v96, v85, v76
	v_add_f32_dpp v92, v93, v93 quad_perm:[2,3,0,1] row_mask:0xf bank_mask:0xf
	v_mul_f32_e32 v97, v85, v77
	v_mul_f32_e32 v98, v85, v78
	v_add_f32_dpp v93, v92, v92 row_ror:4 row_mask:0xf bank_mask:0xf
	v_mul_f32_e32 v99, v85, v79
	s_waitcnt lgkmcnt(6)
	v_fma_f32 v96, v4, v60, v96
	v_fma_f32 v97, v5, v61, v97
	v_add_f32_dpp v94, v93, v93 row_ror:8 row_mask:0xf bank_mask:0xf
	v_add_f32_dpp v111, v93, v93 row_ror:8 row_mask:0xf bank_mask:0x4
	v_fma_f32 v98, v6, v62, v98
	v_fma_f32 v99, v7, v63, v99
	v_add_f32_e32 v105, v90, v91
	s_waitcnt lgkmcnt(5)
	v_fma_f32 v4, -v94, v72, v96
	v_fma_f32 v5, -v94, v73, v97
	v_fma_f32 v6, -v94, v74, v98
	v_fma_f32 v7, -v94, v75, v99
	v_add_f32_dpp v104, v104, v104 row_ror:8 row_mask:0xf bank_mask:0x3
	s_nop 1
	v_add_f32_dpp v104, v105, v105 row_ror:8 row_mask:0xf bank_mask:0xc
	ds_read_b128 v[64:67], v0 offset:19456
	ds_read_b128 v[68:71], v0 offset:19712
	ds_read_b128 v[76:79], v0 offset:20224
	ds_read_b128 v[60:63], v0 offset:19200
	ds_read_b128 v[72:75], v0 offset:19968
	ds_read_b32 v112, v10 offset:0
	ds_read_b64 v[114:115], v11 offset:0
	s_waitcnt lgkmcnt(10)
	v_mul_f32_e32 v88, v4, v44
	v_mul_f32_e32 v89, v6, v48
	v_fma_f32 v88, v5, v46, v88
	v_fma_f32 v89, v7, v50, v89
	v_mul_f32_e32 v90, v4, v45
	v_add_f32_e32 v92, v88, v89
	v_mul_f32_e32 v91, v6, v49
	v_fma_f32 v90, v5, v47, v90
	v_add_f32_dpp v93, v92, v92 quad_perm:[1,0,3,2] row_mask:0xf bank_mask:0xf
	v_fma_f32 v91, v7, v51, v91
	s_waitcnt lgkmcnt(9)
	v_mul_f32_e32 v96, v86, v56
	v_add_f32_dpp v92, v93, v93 quad_perm:[2,3,0,1] row_mask:0xf bank_mask:0xf
	v_mul_f32_e32 v97, v86, v57
	v_mul_f32_e32 v98, v86, v58
	v_add_f32_dpp v93, v92, v92 row_ror:4 row_mask:0xf bank_mask:0xf
	v_mul_f32_e32 v99, v86, v59
	s_waitcnt lgkmcnt(8)
	v_fma_f32 v96, v4, v40, v96
	v_fma_f32 v97, v5, v41, v97
	v_add_f32_dpp v94, v93, v93 row_ror:8 row_mask:0xf bank_mask:0xf
	v_add_f32_dpp v111, v93, v93 row_ror:8 row_mask:0xf bank_mask:0x2
	v_fma_f32 v98, v6, v42, v98
	v_fma_f32 v99, v7, v43, v99
	v_add_f32_e32 v101, v90, v91
	s_waitcnt lgkmcnt(7)
	v_fma_f32 v4, -v94, v52, v96
	v_fma_f32 v5, -v94, v53, v97
	v_fma_f32 v6, -v94, v54, v98
	v_fma_f32 v7, -v94, v55, v99
	s_waitcnt lgkmcnt(5)
	v_mul_f32_e32 v88, v4, v64
	v_mul_f32_e32 v89, v6, v68
	v_fma_f32 v88, v5, v66, v88
	v_fma_f32 v89, v7, v70, v89
	v_mul_f32_e32 v90, v4, v65
	v_add_f32_e32 v92, v88, v89
	v_mul_f32_e32 v91, v6, v69
	v_fma_f32 v90, v5, v67, v90
	v_add_f32_dpp v93, v92, v92 quad_perm:[1,0,3,2] row_mask:0xf bank_mask:0xf
	v_fma_f32 v91, v7, v71, v91
	s_waitcnt lgkmcnt(4)
	v_mul_f32_e32 v96, v87, v76
	v_add_f32_dpp v92, v93, v93 quad_perm:[2,3,0,1] row_mask:0xf bank_mask:0xf
	v_mul_f32_e32 v97, v87, v77
	v_mul_f32_e32 v98, v87, v78
	v_add_f32_dpp v93, v92, v92 row_ror:4 row_mask:0xf bank_mask:0xf
	v_mul_f32_e32 v99, v87, v79
	s_waitcnt lgkmcnt(3)
	v_fma_f32 v96, v4, v60, v96
	v_fma_f32 v97, v5, v61, v97
	v_add_f32_dpp v94, v93, v93 row_ror:8 row_mask:0xf bank_mask:0xf
	v_add_f32_dpp v111, v93, v93 row_ror:8 row_mask:0xf bank_mask:0x8
	v_fma_f32 v98, v6, v62, v98
	v_fma_f32 v99, v7, v63, v99
	v_add_f32_e32 v103, v90, v91
	s_waitcnt lgkmcnt(2)
; __device__ __forceinline__ float bf2f(unsigned short b) { return __uint_as_float(((unsigned)b) << 16); }
; __device__ __forceinline__ unsigned short f2bf(float f) { unsigned r; asm("v_cvt_pk_bf16_f32 %0, %1, %1" : "=v"(r) : "v"(f)); return (unsigned short)(r & 0xffffu); }
; __device__ __forceinline__ float bflo(unsigned u) { return __uint_as_float(u << 16); }
; __device__ __forceinline__ float bfhi(unsigned u) { return __uint_as_float(u & 0xffff0000u); }
; __device__ __forceinline__ float fma_s(float a, float b, float c) { float d; asm("v_fma_f32 %0, %1, %2, %3" : "=v"(d) : "v"(a), "v"(b), "v"(c)); return d; }
; __device__ __forceinline__ float fnma_s(float a, float b, float c) { float d; asm("v_fma_f32 %0, -%1, %2, %3" : "=v"(d) : "v"(a), "v"(b), "v"(c)); return d; }
; __device__ __forceinline__ float sel_eq(float keep, float v, int a, int b) { asm("v_cmp_eq_u32 vcc, %1, %2\n\tv_cndmask_b32 %0, %0, %3, vcc" : "+v"(keep) : "v"(a), "v"(b), "v"(v) : "vcc"); return keep; }
; __device__ __forceinline__ void rwkv_scan2_item(const Params& p, int item, char* ldsraw) {
;     ...
;   auto store = [&](int bi) {
;     float* d = buf + bi * CH + st * STEP;
;     *(f32x4*)(d + part * 4) = pw;
;     *(f32x4*)(d + 64 + part * 4) = (f32x4){bflo(pkk[0]), bfhi(pkk[0]), bflo(pkk[1]), bfhi(pkk[1])};
;     *(f32x4*)(d + 128 + part * 4) = (f32x4){bflo(pkka[0]), bfhi(pkka[0]), bflo(pkka[1]), bfhi(pkka[1])};
;     *(f32x4*)(d + 192 + part * 4) = (f32x4){bflo(pk[0]), bfhi(pk[0]), bflo(pk[1]), bfhi(pk[1])};
;     *(f32x4*)(d + 256 + part * 4) = (f32x4){bflo(pwr[0]), bfhi(pwr[0]), bflo(pwr[1]), bfhi(pwr[1])};
;     d[320 + part] = ident ? 0.f : bf2f(pv);
;     if (part < 2) d[336 + part] = pc;
;   };
;     ...
;           const float yA = fnma_s(psA, ccc.x, fma_s(cvA, ccc.y, puA)), yB = fnma_s(psB, ccc.x, fma_s(cvB, ccc.y, puB));
;           ykA = sel_eq(ykA, yA, jl, q); ykB = sel_eq(ykB, yB, jl, q);
;         }
;     ...
;         yout[(size_t)(c - 1) * ystride] = f2bf(ykA); yout[(size_t)(c - 1) * ystride + 8] = f2bf(ykB);
;       }
;     }
;     if (c + 1 < 128) store(bnext);
;     bi = bnext;
;     asm volatile("s_waitcnt lgkmcnt(0)" ::: "memory"); __builtin_amdgcn_s_barrier(); asm volatile("" ::: "memory");
	v_fma_f32 v4, -v94, v72, v96
	v_fma_f32 v5, -v94, v73, v97
	v_fma_f32 v6, -v94, v74, v98
	v_fma_f32 v7, -v94, v75, v99
	v_add_f32_dpp v101, v101, v101 row_ror:8 row_mask:0xf bank_mask:0x3
	s_nop 1
	v_add_f32_dpp v101, v103, v103 row_ror:8 row_mask:0xf bank_mask:0xc
	v_add_f32_dpp v104, v104, v104 row_half_mirror row_mask:0xf bank_mask:0x5
	s_nop 1
	v_add_f32_dpp v104, v101, v101 row_half_mirror row_mask:0xf bank_mask:0xa
	v_cndmask_b32_e64 v106, v104, v102, s[36:37]
	v_cndmask_b32_e64 v107, v102, v104, s[36:37]
	s_nop 1
	v_add_f32_dpp v102, v106, v107 quad_perm:[2,3,0,1] row_mask:0xf bank_mask:0xf
	v_cndmask_b32_e64 v106, v102, v100, s[34:35]
	v_cndmask_b32_e64 v107, v100, v102, s[34:35]
	s_nop 1
	v_add_f32_dpp v100, v106, v107 quad_perm:[1,0,3,2] row_mask:0xf bank_mask:0xf
	v_cndmask_b32_e64 v106, v108, v110, s[34:35]
	v_cndmask_b32_e64 v107, v109, v111, s[34:35]
	v_cndmask_b32_e64 v106, v106, v107, s[36:37]
	s_waitcnt lgkmcnt(0)
	v_fma_f32 v100, v112, v115, v100
	v_fma_f32 v100, -v106, v114, v100
	v_cvt_pk_bf16_f32 v107, v100, v100
	global_store_short v16, v107, s[30:31]
	s_waitcnt vmcnt(1)
	ds_write_b128 v2, v[20:23] offset:21632
	v_lshlrev_b32_e32 v36, 16, v24
	v_lshlrev_b32_e32 v37, 16, v30
	v_and_b32_e32 v38, 0xffff0000, v24
	v_and_b32_e32 v39, 0xffff0000, v30
	ds_write_b128 v2, v[36:39] offset:21888
	v_lshlrev_b32_e32 v40, 16, v25
	v_lshlrev_b32_e32 v41, 16, v31
	v_and_b32_e32 v42, 0xffff0000, v25
	v_and_b32_e32 v43, 0xffff0000, v31
	ds_write_b128 v2, v[40:43] offset:22144
	v_lshlrev_b32_e32 v44, 16, v26
	v_and_b32_e32 v45, 0xffff0000, v26
	v_lshlrev_b32_e32 v46, 16, v27
	v_and_b32_e32 v47, 0xffff0000, v27
	ds_write_b128 v2, v[44:47] offset:22400
	v_lshlrev_b32_e32 v48, 16, v28
	v_and_b32_e32 v49, 0xffff0000, v28
	v_lshlrev_b32_e32 v50, 16, v29
	v_and_b32_e32 v51, 0xffff0000, v29
	ds_write_b128 v2, v[48:51] offset:22656
	v_lshlrev_b32_e32 v52, 16, v32
	s_cmp_eq_u32 s41, 2
	s_cselect_b32 s2, 0, -1
	v_and_b32_e32 v52, s2, v52
	ds_write_b32 v8, v52 offset:21632
	s_mov_b32 s2, 0x00010001
	s_mov_b32 s3, 0x00010001
	s_mov_b64 exec, s[2:3]
	ds_write_b64 v9, v[34:35] offset:21632
	s_mov_b64 exec, -1
	s_add_u32 s24, s24, 0x1000
	s_addc_u32 s25, s25, 0
	s_add_u32 s26, s26, 0x2800
	s_addc_u32 s27, s27, 0
	s_add_u32 s28, s28, 0x100
	s_addc_u32 s29, s29, 0
	s_add_u32 s30, s30, s40
	s_addc_u32 s31, s31, 0
	s_waitcnt lgkmcnt(0)
	s_barrier
	s_cmp_eq_u32 s38, 63
	s_cbranch_scc1 .Lsc_o_nold
	global_load_dwordx4 v[20:23], v12, s[24:25]
	global_load_dwordx2 v[24:25], v13, s[26:27]
	global_load_dwordx2 v[26:27], v13, s[26:27] offset:128
	global_load_dwordx2 v[28:29], v13, s[26:27] offset:256
	global_load_dwordx2 v[30:31], v13, s[26:27] offset:384
	global_load_ushort v32, v14, s[26:27]
	global_load_dwordx2 v[34:35], v15, s[28:29]
.Lsc_o_nold:
	ds_read_b128 v[44:47], v0 offset:21888
	ds_read_b128 v[48:51], v0 offset:22144
	ds_read_b128 v[56:59], v0 offset:22656
	ds_read_b128 v[40:43], v0 offset:21632
	ds_read_b128 v[52:55], v0 offset:22400
	ds_read_b128 v[80:83], v1 offset:21632
	ds_read_b128 v[64:67], v0 offset:23168
	ds_read_b128 v[68:71], v0 offset:23424
	ds_read_b128 v[76:79], v0 offset:23936
	ds_read_b128 v[60:63], v0 offset:22912
	ds_read_b128 v[72:75], v0 offset:23680
	s_waitcnt lgkmcnt(9)
	v_mul_f32_e32 v88, v4, v44
	v_mul_f32_e32 v89, v6, v48
	v_fma_f32 v88, v5, v46, v88
	v_fma_f32 v89, v7, v50, v89
	v_mul_f32_e32 v90, v4, v45
	v_add_f32_e32 v92, v88, v89
	v_mul_f32_e32 v91, v6, v49
	v_fma_f32 v90, v5, v47, v90
	v_add_f32_dpp v93, v92, v92 quad_perm:[1,0,3,2] row_mask:0xf bank_mask:0xf
	v_fma_f32 v91, v7, v51, v91
	s_waitcnt lgkmcnt(5)
	v_mul_f32_e32 v96, v80, v56
	v_add_f32_dpp v92, v93, v93 quad_perm:[2,3,0,1] row_mask:0xf bank_mask:0xf
	v_mul_f32_e32 v97, v80, v57
	v_mul_f32_e32 v98, v80, v58
	v_add_f32_dpp v93, v92, v92 row_ror:4 row_mask:0xf bank_mask:0xf
	v_mul_f32_e32 v99, v80, v59
	v_fma_f32 v96, v4, v40, v96
	v_fma_f32 v97, v5, v41, v97
	v_add_f32_dpp v94, v93, v93 row_ror:8 row_mask:0xf bank_mask:0xf
	v_add_f32_dpp v108, v93, v93 row_ror:8 row_mask:0xf bank_mask:0x1
	v_fma_f32 v98, v6, v42, v98
	v_fma_f32 v99, v7, v43, v99
	v_add_f32_e32 v100, v90, v91
	v_fma_f32 v4, -v94, v52, v96
	v_fma_f32 v5, -v94, v53, v97
	v_fma_f32 v6, -v94, v54, v98
	v_fma_f32 v7, -v94, v55, v99
	ds_read_b128 v[44:47], v0 offset:24448
	ds_read_b128 v[48:51], v0 offset:24704
	ds_read_b128 v[56:59], v0 offset:25216
	ds_read_b128 v[40:43], v0 offset:24192
	ds_read_b128 v[52:55], v0 offset:24960
	s_waitcnt lgkmcnt(8)
	v_mul_f32_e32 v88, v4, v64
	v_mul_f32_e32 v89, v6, v68
	v_fma_f32 v88, v5, v66, v88
	v_fma_f32 v89, v7, v70, v89
	v_mul_f32_e32 v90, v4, v65
	v_add_f32_e32 v92, v88, v89
	v_mul_f32_e32 v91, v6, v69
	v_fma_f32 v90, v5, v67, v90
	v_add_f32_dpp v93, v92, v92 quad_perm:[1,0,3,2] row_mask:0xf bank_mask:0xf
	v_fma_f32 v91, v7, v71, v91
	s_waitcnt lgkmcnt(7)
	v_mul_f32_e32 v96, v81, v76
	v_add_f32_dpp v92, v93, v93 quad_perm:[2,3,0,1] row_mask:0xf bank_mask:0xf
	v_mul_f32_e32 v97, v81, v77
	v_mul_f32_e32 v98, v81, v78
	v_add_f32_dpp v93, v92, v92 row_ror:4 row_mask:0xf bank_mask:0xf
	v_mul_f32_e32 v99, v81, v79
	s_waitcnt lgkmcnt(6)
	v_fma_f32 v96, v4, v60, v96
	v_fma_f32 v97, v5, v61, v97
	v_add_f32_dpp v94, v93, v93 row_ror:8 row_mask:0xf bank_mask:0xf
	v_add_f32_dpp v108, v93, v93 row_ror:8 row_mask:0xf bank_mask:0x4
	v_fma_f32 v98, v6, v62, v98
	v_fma_f32 v99, v7, v63, v99
	v_add_f32_e32 v101, v90, v91
	s_waitcnt lgkmcnt(5)
; __device__ __forceinline__ void rwkv_scan2_item(const Params& p, int item, char* ldsraw) {
;     ...
;         for (int q = 0; q < 16; q++) {
;           const f32x4 cw = nw, ckk = nkk, ckka = nkka, ck = nk; const float cvA = nvA, cvB = nvB;
;           if (q < 15) R_LOAD(q + 1)
;           __builtin_amdgcn_sched_barrier(0);
;           float mA0 = mul_s(a0, ckk.x), mA1 = mul_s(a2, ckk.z), mB0 = mul_s(b0, ckk.x), mB1 = mul_s(b2, ckk.z);
;           mA0 = fma_s(a1, ckk.y, mA0); mA1 = fma_s(a3, ckk.w, mA1); mB0 = fma_s(b1, ckk.y, mB0); mB1 = fma_s(b3, ckk.w, mB1);
;           float psA = add_s(mA0, mA1), psB = add_s(mB0, mB1);
;           psA = row16_sum(psA); psB = row16_sum(psB);
;           { const float t0 = fnma_s(psA, ckka.x, mul_s(cvA, ck.x)), t1 = fnma_s(psA, ckka.y, mul_s(cvA, ck.y));
;             const float t2 = fnma_s(psA, ckka.z, mul_s(cvA, ck.z)), t3 = fnma_s(psA, ckka.w, mul_s(cvA, ck.w));
;             a0 = fma_s(a0, cw.x, t0); a1 = fma_s(a1, cw.y, t1); a2 = fma_s(a2, cw.z, t2); a3 = fma_s(a3, cw.w, t3); }
;           { const float t0 = fnma_s(psB, ckka.x, mul_s(cvB, ck.x)), t1 = fnma_s(psB, ckka.y, mul_s(cvB, ck.y));
;             const float t2 = fnma_s(psB, ckka.z, mul_s(cvB, ck.z)), t3 = fnma_s(psB, ckka.w, mul_s(cvB, ck.w));
;             b0 = fma_s(b0, cw.x, t0); b1 = fma_s(b1, cw.y, t1); b2 = fma_s(b2, cw.z, t2); b3 = fma_s(b3, cw.w, t3); }
;           sakA = sel_eq(sakA, psA, jl, q); sakB = sel_eq(sakB, psB, jl, q);
;         }
;     ...
;         SA[(c & 1) * 256 + jl * 16 + row8] = sakA; SA[(c & 1) * 256 + jl * 16 + 8 + row8] = sakB;
;       }
;     } else {
;       if (c >= 1) {
;         const float* d = buf + bprev * CH + jl * 4;
;         const float* dvp = buf + bprev * CH + 320 + row8;
;         const float* dcp = buf + bprev * CH + 336;
;         const float* sap = SA + ((c - 1) & 1) * 256 + row8;
;         f32x4 nw, nkka, nk, nwr; float nvA, nvB, nsA, nsB; f32x2 ncc;
;     ...
;         Y_LOAD(0)
;         float ykA = 0.f, ykB = 0.f;
; #pragma unroll
;         for (int q = 0; q < 16; q++) {
;           const f32x4 cw = nw, ckka = nkka, ck = nk, cwr = nwr; const float cvA = nvA, cvB = nvB, psA = nsA, psB = nsB; const f32x2 ccc = ncc;
;           if (q < 15) Y_LOAD(q + 1)
;           __builtin_amdgcn_sched_barrier(0);
;           float nA0 = mul_s(a0, cwr.x), nA1 = mul_s(a2, cwr.z), nB0 = mul_s(b0, cwr.x), nB1 = mul_s(b2, cwr.z);
	v_fma_f32 v4, -v94, v72, v96
	v_fma_f32 v5, -v94, v73, v97
	v_fma_f32 v6, -v94, v74, v98
	v_fma_f32 v7, -v94, v75, v99
	v_add_f32_dpp v100, v100, v100 row_ror:8 row_mask:0xf bank_mask:0x3
	s_nop 1
	v_add_f32_dpp v100, v101, v101 row_ror:8 row_mask:0xf bank_mask:0xc
	ds_read_b128 v[64:67], v0 offset:25728
	ds_read_b128 v[68:71], v0 offset:25984
	ds_read_b128 v[76:79], v0 offset:26496
	ds_read_b128 v[60:63], v0 offset:25472
	ds_read_b128 v[72:75], v0 offset:26240
	s_waitcnt lgkmcnt(8)
	v_mul_f32_e32 v88, v4, v44
	v_mul_f32_e32 v89, v6, v48
	v_fma_f32 v88, v5, v46, v88
	v_fma_f32 v89, v7, v50, v89
	v_mul_f32_e32 v90, v4, v45
	v_add_f32_e32 v92, v88, v89
	v_mul_f32_e32 v91, v6, v49
	v_fma_f32 v90, v5, v47, v90
	v_add_f32_dpp v93, v92, v92 quad_perm:[1,0,3,2] row_mask:0xf bank_mask:0xf
	v_fma_f32 v91, v7, v51, v91
	s_waitcnt lgkmcnt(7)
	v_mul_f32_e32 v96, v82, v56
	v_add_f32_dpp v92, v93, v93 quad_perm:[2,3,0,1] row_mask:0xf bank_mask:0xf
	v_mul_f32_e32 v97, v82, v57
	v_mul_f32_e32 v98, v82, v58
	v_add_f32_dpp v93, v92, v92 row_ror:4 row_mask:0xf bank_mask:0xf
	v_mul_f32_e32 v99, v82, v59
	s_waitcnt lgkmcnt(6)
	v_fma_f32 v96, v4, v40, v96
	v_fma_f32 v97, v5, v41, v97
	v_add_f32_dpp v94, v93, v93 row_ror:8 row_mask:0xf bank_mask:0xf
	v_add_f32_dpp v108, v93, v93 row_ror:8 row_mask:0xf bank_mask:0x2
	v_fma_f32 v98, v6, v42, v98
	v_fma_f32 v99, v7, v43, v99
	v_add_f32_e32 v102, v90, v91
	s_waitcnt lgkmcnt(5)
	v_fma_f32 v4, -v94, v52, v96
	v_fma_f32 v5, -v94, v53, v97
	v_fma_f32 v6, -v94, v54, v98
	v_fma_f32 v7, -v94, v55, v99
	ds_read_b128 v[44:47], v0 offset:27008
	ds_read_b128 v[48:51], v0 offset:27264
	ds_read_b128 v[56:59], v0 offset:27776
	ds_read_b128 v[40:43], v0 offset:26752
	ds_read_b128 v[52:55], v0 offset:27520
	ds_read_b128 v[84:87], v1 offset:21648
	s_waitcnt lgkmcnt(9)
	v_mul_f32_e32 v88, v4, v64
	v_mul_f32_e32 v89, v6, v68
	v_fma_f32 v88, v5, v66, v88
	v_fma_f32 v89, v7, v70, v89
	v_mul_f32_e32 v90, v4, v65
	v_add_f32_e32 v92, v88, v89
	v_mul_f32_e32 v91, v6, v69
	v_fma_f32 v90, v5, v67, v90
	v_add_f32_dpp v93, v92, v92 quad_perm:[1,0,3,2] row_mask:0xf bank_mask:0xf
	v_fma_f32 v91, v7, v71, v91
	s_waitcnt lgkmcnt(8)
	v_mul_f32_e32 v96, v83, v76
	v_add_f32_dpp v92, v93, v93 quad_perm:[2,3,0,1] row_mask:0xf bank_mask:0xf
	v_mul_f32_e32 v97, v83, v77
	v_mul_f32_e32 v98, v83, v78
	v_add_f32_dpp v93, v92, v92 row_ror:4 row_mask:0xf bank_mask:0xf
	v_mul_f32_e32 v99, v83, v79
	s_waitcnt lgkmcnt(7)
	v_fma_f32 v96, v4, v60, v96
	v_fma_f32 v97, v5, v61, v97
	v_add_f32_dpp v94, v93, v93 row_ror:8 row_mask:0xf bank_mask:0xf
	v_add_f32_dpp v108, v93, v93 row_ror:8 row_mask:0xf bank_mask:0x8
	v_fma_f32 v98, v6, v62, v98
	v_fma_f32 v99, v7, v63, v99
	v_add_f32_e32 v103, v90, v91
	s_waitcnt lgkmcnt(6)
	v_fma_f32 v4, -v94, v72, v96
	v_fma_f32 v5, -v94, v73, v97
	v_fma_f32 v6, -v94, v74, v98
	v_fma_f32 v7, -v94, v75, v99
	v_add_f32_dpp v102, v102, v102 row_ror:8 row_mask:0xf bank_mask:0x3
	s_nop 1
	v_add_f32_dpp v102, v103, v103 row_ror:8 row_mask:0xf bank_mask:0xc
	v_add_f32_dpp v100, v100, v100 row_half_mirror row_mask:0xf bank_mask:0x5
	s_nop 1
	v_add_f32_dpp v100, v102, v102 row_half_mirror row_mask:0xf bank_mask:0xa
	ds_read_b128 v[64:67], v0 offset:28288
	ds_read_b128 v[68:71], v0 offset:28544
	ds_read_b128 v[76:79], v0 offset:29056
	ds_read_b128 v[60:63], v0 offset:28032
	ds_read_b128 v[72:75], v0 offset:28800
	s_waitcnt lgkmcnt(9)
	v_mul_f32_e32 v88, v4, v44
	v_mul_f32_e32 v89, v6, v48
	v_fma_f32 v88, v5, v46, v88
	v_fma_f32 v89, v7, v50, v89
	v_mul_f32_e32 v90, v4, v45
	v_add_f32_e32 v92, v88, v89
	v_mul_f32_e32 v91, v6, v49
	v_fma_f32 v90, v5, v47, v90
	v_add_f32_dpp v93, v92, v92 quad_perm:[1,0,3,2] row_mask:0xf bank_mask:0xf
	v_fma_f32 v91, v7, v51, v91
	s_waitcnt lgkmcnt(5)
	v_mul_f32_e32 v96, v84, v56
	v_add_f32_dpp v92, v93, v93 quad_perm:[2,3,0,1] row_mask:0xf bank_mask:0xf
	v_mul_f32_e32 v97, v84, v57
	v_mul_f32_e32 v98, v84, v58
	v_add_f32_dpp v93, v92, v92 row_ror:4 row_mask:0xf bank_mask:0xf
	v_mul_f32_e32 v99, v84, v59
	v_fma_f32 v96, v4, v40, v96
	v_fma_f32 v97, v5, v41, v97
	v_add_f32_dpp v94, v93, v93 row_ror:8 row_mask:0xf bank_mask:0xf
	v_add_f32_dpp v109, v93, v93 row_ror:8 row_mask:0xf bank_mask:0x1
	v_fma_f32 v98, v6, v42, v98
	v_fma_f32 v99, v7, v43, v99
	v_add_f32_e32 v104, v90, v91
	v_fma_f32 v4, -v94, v52, v96
	v_fma_f32 v5, -v94, v53, v97
	v_fma_f32 v6, -v94, v54, v98
	v_fma_f32 v7, -v94, v55, v99
	ds_read_b128 v[44:47], v0 offset:29568
	ds_read_b128 v[48:51], v0 offset:29824
	ds_read_b128 v[56:59], v0 offset:30336
	ds_read_b128 v[40:43], v0 offset:29312
	ds_read_b128 v[52:55], v0 offset:30080
	s_waitcnt lgkmcnt(8)
	v_mul_f32_e32 v88, v4, v64
	v_mul_f32_e32 v89, v6, v68
	v_fma_f32 v88, v5, v66, v88
	v_fma_f32 v89, v7, v70, v89
	v_mul_f32_e32 v90, v4, v65
	v_add_f32_e32 v92, v88, v89
	v_mul_f32_e32 v91, v6, v69
	v_fma_f32 v90, v5, v67, v90
	v_add_f32_dpp v93, v92, v92 quad_perm:[1,0,3,2] row_mask:0xf bank_mask:0xf
	v_fma_f32 v91, v7, v71, v91
	s_waitcnt lgkmcnt(7)
	v_mul_f32_e32 v96, v85, v76
	v_add_f32_dpp v92, v93, v93 quad_perm:[2,3,0,1] row_mask:0xf bank_mask:0xf
	v_mul_f32_e32 v97, v85, v77
	v_mul_f32_e32 v98, v85, v78
	v_add_f32_dpp v93, v92, v92 row_ror:4 row_mask:0xf bank_mask:0xf
	v_mul_f32_e32 v99, v85, v79
	s_waitcnt lgkmcnt(6)
	v_fma_f32 v96, v4, v60, v96
	v_fma_f32 v97, v5, v61, v97
	v_add_f32_dpp v94, v93, v93 row_ror:8 row_mask:0xf bank_mask:0xf
	v_add_f32_dpp v109, v93, v93 row_ror:8 row_mask:0xf bank_mask:0x4
	v_fma_f32 v98, v6, v62, v98
	v_fma_f32 v99, v7, v63, v99
	v_add_f32_e32 v105, v90, v91
	s_waitcnt lgkmcnt(5)
; __device__ __forceinline__ void rwkv_scan2_item(const Params& p, int item, char* ldsraw) {
;     ...
;         for (int q = 0; q < 16; q++) {
;           const f32x4 cw = nw, ckk = nkk, ckka = nkka, ck = nk; const float cvA = nvA, cvB = nvB;
;           if (q < 15) R_LOAD(q + 1)
;           __builtin_amdgcn_sched_barrier(0);
;           float mA0 = mul_s(a0, ckk.x), mA1 = mul_s(a2, ckk.z), mB0 = mul_s(b0, ckk.x), mB1 = mul_s(b2, ckk.z);
;           mA0 = fma_s(a1, ckk.y, mA0); mA1 = fma_s(a3, ckk.w, mA1); mB0 = fma_s(b1, ckk.y, mB0); mB1 = fma_s(b3, ckk.w, mB1);
;           float psA = add_s(mA0, mA1), psB = add_s(mB0, mB1);
;           psA = row16_sum(psA); psB = row16_sum(psB);
;           { const float t0 = fnma_s(psA, ckka.x, mul_s(cvA, ck.x)), t1 = fnma_s(psA, ckka.y, mul_s(cvA, ck.y));
;             const float t2 = fnma_s(psA, ckka.z, mul_s(cvA, ck.z)), t3 = fnma_s(psA, ckka.w, mul_s(cvA, ck.w));
;             a0 = fma_s(a0, cw.x, t0); a1 = fma_s(a1, cw.y, t1); a2 = fma_s(a2, cw.z, t2); a3 = fma_s(a3, cw.w, t3); }
;           { const float t0 = fnma_s(psB, ckka.x, mul_s(cvB, ck.x)), t1 = fnma_s(psB, ckka.y, mul_s(cvB, ck.y));
;             const float t2 = fnma_s(psB, ckka.z, mul_s(cvB, ck.z)), t3 = fnma_s(psB, ckka.w, mul_s(cvB, ck.w));
;             b0 = fma_s(b0, cw.x, t0); b1 = fma_s(b1, cw.y, t1); b2 = fma_s(b2, cw.z, t2); b3 = fma_s(b3, cw.w, t3); }
;           sakA = sel_eq(sakA, psA, jl, q); sakB = sel_eq(sakB, psB, jl, q);
;         }
;     ...
;         SA[(c & 1) * 256 + jl * 16 + row8] = sakA; SA[(c & 1) * 256 + jl * 16 + 8 + row8] = sakB;
;       }
;     } else {
;       if (c >= 1) {
;         const float* d = buf + bprev * CH + jl * 4;
;         const float* dvp = buf + bprev * CH + 320 + row8;
;         const float* dcp = buf + bprev * CH + 336;
;         const float* sap = SA + ((c - 1) & 1) * 256 + row8;
;         f32x4 nw, nkka, nk, nwr; float nvA, nvB, nsA, nsB; f32x2 ncc;
;     ...
;         Y_LOAD(0)
;         float ykA = 0.f, ykB = 0.f;
; #pragma unroll
;         for (int q = 0; q < 16; q++) {
;           const f32x4 cw = nw, ckka = nkka, ck = nk, cwr = nwr; const float cvA = nvA, cvB = nvB, psA = nsA, psB = nsB; const f32x2 ccc = ncc;
;           if (q < 15) Y_LOAD(q + 1)
;           __builtin_amdgcn_sched_barrier(0);
;           float nA0 = mul_s(a0, cwr.x), nA1 = mul_s(a2, cwr.z), nB0 = mul_s(b0, cwr.x), nB1 = mul_s(b2, cwr.z);
	v_fma_f32 v4, -v94, v72, v96
	v_fma_f32 v5, -v94, v73, v97
	v_fma_f32 v6, -v94, v74, v98
	v_fma_f32 v7, -v94, v75, v99
	v_add_f32_dpp v104, v104, v104 row_ror:8 row_mask:0xf bank_mask:0x3
	s_nop 1
	v_add_f32_dpp v104, v105, v105 row_ror:8 row_mask:0xf bank_mask:0xc
	ds_read_b128 v[64:67], v0 offset:30848
	ds_read_b128 v[68:71], v0 offset:31104
	ds_read_b128 v[76:79], v0 offset:31616
	ds_read_b128 v[60:63], v0 offset:30592
	ds_read_b128 v[72:75], v0 offset:31360
	s_waitcnt lgkmcnt(8)
	v_mul_f32_e32 v88, v4, v44
	v_mul_f32_e32 v89, v6, v48
	v_fma_f32 v88, v5, v46, v88
	v_fma_f32 v89, v7, v50, v89
	v_mul_f32_e32 v90, v4, v45
	v_add_f32_e32 v92, v88, v89
	v_mul_f32_e32 v91, v6, v49
	v_fma_f32 v90, v5, v47, v90
	v_add_f32_dpp v93, v92, v92 quad_perm:[1,0,3,2] row_mask:0xf bank_mask:0xf
	v_fma_f32 v91, v7, v51, v91
	s_waitcnt lgkmcnt(7)
	v_mul_f32_e32 v96, v86, v56
	v_add_f32_dpp v92, v93, v93 quad_perm:[2,3,0,1] row_mask:0xf bank_mask:0xf
	v_mul_f32_e32 v97, v86, v57
	v_mul_f32_e32 v98, v86, v58
	v_add_f32_dpp v93, v92, v92 row_ror:4 row_mask:0xf bank_mask:0xf
	v_mul_f32_e32 v99, v86, v59
	s_waitcnt lgkmcnt(6)
	v_fma_f32 v96, v4, v40, v96
	v_fma_f32 v97, v5, v41, v97
	v_add_f32_dpp v94, v93, v93 row_ror:8 row_mask:0xf bank_mask:0xf
	v_add_f32_dpp v109, v93, v93 row_ror:8 row_mask:0xf bank_mask:0x2
	v_fma_f32 v98, v6, v42, v98
	v_fma_f32 v99, v7, v43, v99
	v_add_f32_e32 v101, v90, v91
	s_waitcnt lgkmcnt(5)
	v_fma_f32 v4, -v94, v52, v96
	v_fma_f32 v5, -v94, v53, v97
	v_fma_f32 v6, -v94, v54, v98
	v_fma_f32 v7, -v94, v55, v99
	ds_read_b128 v[44:47], v0 offset:32128
	ds_read_b128 v[48:51], v0 offset:32384
	ds_read_b128 v[56:59], v0 offset:32896
	ds_read_b128 v[40:43], v0 offset:31872
	ds_read_b128 v[52:55], v0 offset:32640
	ds_read_b128 v[80:83], v1 offset:21664
	s_waitcnt lgkmcnt(9)
	v_mul_f32_e32 v88, v4, v64
	v_mul_f32_e32 v89, v6, v68
	v_fma_f32 v88, v5, v66, v88
	v_fma_f32 v89, v7, v70, v89
	v_mul_f32_e32 v90, v4, v65
	v_add_f32_e32 v92, v88, v89
	v_mul_f32_e32 v91, v6, v69
	v_fma_f32 v90, v5, v67, v90
	v_add_f32_dpp v93, v92, v92 quad_perm:[1,0,3,2] row_mask:0xf bank_mask:0xf
	v_fma_f32 v91, v7, v71, v91
	s_waitcnt lgkmcnt(8)
	v_mul_f32_e32 v96, v87, v76
	v_add_f32_dpp v92, v93, v93 quad_perm:[2,3,0,1] row_mask:0xf bank_mask:0xf
	v_mul_f32_e32 v97, v87, v77
	v_mul_f32_e32 v98, v87, v78
	v_add_f32_dpp v93, v92, v92 row_ror:4 row_mask:0xf bank_mask:0xf
	v_mul_f32_e32 v99, v87, v79
	s_waitcnt lgkmcnt(7)
	v_fma_f32 v96, v4, v60, v96
	v_fma_f32 v97, v5, v61, v97
	v_add_f32_dpp v94, v93, v93 row_ror:8 row_mask:0xf bank_mask:0xf
	v_add_f32_dpp v109, v93, v93 row_ror:8 row_mask:0xf bank_mask:0x8
	v_fma_f32 v98, v6, v62, v98
	v_fma_f32 v99, v7, v63, v99
	v_add_f32_e32 v103, v90, v91
	s_waitcnt lgkmcnt(6)
	v_fma_f32 v4, -v94, v72, v96
	v_fma_f32 v5, -v94, v73, v97
	v_fma_f32 v6, -v94, v74, v98
	v_fma_f32 v7, -v94, v75, v99
	v_add_f32_dpp v101, v101, v101 row_ror:8 row_mask:0xf bank_mask:0x3
	s_nop 1
	v_add_f32_dpp v101, v103, v103 row_ror:8 row_mask:0xf bank_mask:0xc
	v_add_f32_dpp v104, v104, v104 row_half_mirror row_mask:0xf bank_mask:0x5
	s_nop 1
	v_add_f32_dpp v104, v101, v101 row_half_mirror row_mask:0xf bank_mask:0xa
	v_cndmask_b32_e64 v106, v104, v100, s[36:37]
	v_cndmask_b32_e64 v107, v100, v104, s[36:37]
	s_nop 1
	v_add_f32_dpp v100, v106, v107 quad_perm:[2,3,0,1] row_mask:0xf bank_mask:0xf
	ds_read_b128 v[64:67], v0 offset:33408
	ds_read_b128 v[68:71], v0 offset:33664
	ds_read_b128 v[76:79], v0 offset:34176
	ds_read_b128 v[60:63], v0 offset:33152
	ds_read_b128 v[72:75], v0 offset:33920
	s_waitcnt lgkmcnt(9)
	v_mul_f32_e32 v88, v4, v44
	v_mul_f32_e32 v89, v6, v48
	v_fma_f32 v88, v5, v46, v88
	v_fma_f32 v89, v7, v50, v89
	v_mul_f32_e32 v90, v4, v45
	v_add_f32_e32 v92, v88, v89
	v_mul_f32_e32 v91, v6, v49
	v_fma_f32 v90, v5, v47, v90
	v_add_f32_dpp v93, v92, v92 quad_perm:[1,0,3,2] row_mask:0xf bank_mask:0xf
	v_fma_f32 v91, v7, v51, v91
	s_waitcnt lgkmcnt(5)
	v_mul_f32_e32 v96, v80, v56
	v_add_f32_dpp v92, v93, v93 quad_perm:[2,3,0,1] row_mask:0xf bank_mask:0xf
	v_mul_f32_e32 v97, v80, v57
	v_mul_f32_e32 v98, v80, v58
	v_add_f32_dpp v93, v92, v92 row_ror:4 row_mask:0xf bank_mask:0xf
	v_mul_f32_e32 v99, v80, v59
	v_fma_f32 v96, v4, v40, v96
	v_fma_f32 v97, v5, v41, v97
	v_add_f32_dpp v94, v93, v93 row_ror:8 row_mask:0xf bank_mask:0xf
	v_add_f32_dpp v110, v93, v93 row_ror:8 row_mask:0xf bank_mask:0x1
	v_fma_f32 v98, v6, v42, v98
	v_fma_f32 v99, v7, v43, v99
	v_add_f32_e32 v102, v90, v91
	v_fma_f32 v4, -v94, v52, v96
	v_fma_f32 v5, -v94, v53, v97
	v_fma_f32 v6, -v94, v54, v98
	v_fma_f32 v7, -v94, v55, v99
	ds_read_b128 v[44:47], v0 offset:34688
	ds_read_b128 v[48:51], v0 offset:34944
	ds_read_b128 v[56:59], v0 offset:35456
	ds_read_b128 v[40:43], v0 offset:34432
	ds_read_b128 v[52:55], v0 offset:35200
	s_waitcnt lgkmcnt(8)
	v_mul_f32_e32 v88, v4, v64
	v_mul_f32_e32 v89, v6, v68
	v_fma_f32 v88, v5, v66, v88
	v_fma_f32 v89, v7, v70, v89
	v_mul_f32_e32 v90, v4, v65
	v_add_f32_e32 v92, v88, v89
	v_mul_f32_e32 v91, v6, v69
	v_fma_f32 v90, v5, v67, v90
	v_add_f32_dpp v93, v92, v92 quad_perm:[1,0,3,2] row_mask:0xf bank_mask:0xf
	v_fma_f32 v91, v7, v71, v91
	s_waitcnt lgkmcnt(7)
	v_mul_f32_e32 v96, v81, v76
	v_add_f32_dpp v92, v93, v93 quad_perm:[2,3,0,1] row_mask:0xf bank_mask:0xf
	v_mul_f32_e32 v97, v81, v77
	v_mul_f32_e32 v98, v81, v78
	v_add_f32_dpp v93, v92, v92 row_ror:4 row_mask:0xf bank_mask:0xf
	v_mul_f32_e32 v99, v81, v79
	s_waitcnt lgkmcnt(6)
	v_fma_f32 v96, v4, v60, v96
	v_fma_f32 v97, v5, v61, v97
	v_add_f32_dpp v94, v93, v93 row_ror:8 row_mask:0xf bank_mask:0xf
	v_add_f32_dpp v110, v93, v93 row_ror:8 row_mask:0xf bank_mask:0x4
	v_fma_f32 v98, v6, v62, v98
	v_fma_f32 v99, v7, v63, v99
	v_add_f32_e32 v105, v90, v91
	s_waitcnt lgkmcnt(5)
; __device__ __forceinline__ void rwkv_scan2_item(const Params& p, int item, char* ldsraw) {
;     ...
;         for (int q = 0; q < 16; q++) {
;           const f32x4 cw = nw, ckk = nkk, ckka = nkka, ck = nk; const float cvA = nvA, cvB = nvB;
;           if (q < 15) R_LOAD(q + 1)
;           __builtin_amdgcn_sched_barrier(0);
;           float mA0 = mul_s(a0, ckk.x), mA1 = mul_s(a2, ckk.z), mB0 = mul_s(b0, ckk.x), mB1 = mul_s(b2, ckk.z);
;           mA0 = fma_s(a1, ckk.y, mA0); mA1 = fma_s(a3, ckk.w, mA1); mB0 = fma_s(b1, ckk.y, mB0); mB1 = fma_s(b3, ckk.w, mB1);
;           float psA = add_s(mA0, mA1), psB = add_s(mB0, mB1);
;           psA = row16_sum(psA); psB = row16_sum(psB);
;           { const float t0 = fnma_s(psA, ckka.x, mul_s(cvA, ck.x)), t1 = fnma_s(psA, ckka.y, mul_s(cvA, ck.y));
;             const float t2 = fnma_s(psA, ckka.z, mul_s(cvA, ck.z)), t3 = fnma_s(psA, ckka.w, mul_s(cvA, ck.w));
;             a0 = fma_s(a0, cw.x, t0); a1 = fma_s(a1, cw.y, t1); a2 = fma_s(a2, cw.z, t2); a3 = fma_s(a3, cw.w, t3); }
;           { const float t0 = fnma_s(psB, ckka.x, mul_s(cvB, ck.x)), t1 = fnma_s(psB, ckka.y, mul_s(cvB, ck.y));
;             const float t2 = fnma_s(psB, ckka.z, mul_s(cvB, ck.z)), t3 = fnma_s(psB, ckka.w, mul_s(cvB, ck.w));
;             b0 = fma_s(b0, cw.x, t0); b1 = fma_s(b1, cw.y, t1); b2 = fma_s(b2, cw.z, t2); b3 = fma_s(b3, cw.w, t3); }
;           sakA = sel_eq(sakA, psA, jl, q); sakB = sel_eq(sakB, psB, jl, q);
;         }
;     ...
;         SA[(c & 1) * 256 + jl * 16 + row8] = sakA; SA[(c & 1) * 256 + jl * 16 + 8 + row8] = sakB;
;       }
;     } else {
;       if (c >= 1) {
;         const float* d = buf + bprev * CH + jl * 4;
;         const float* dvp = buf + bprev * CH + 320 + row8;
;         const float* dcp = buf + bprev * CH + 336;
;         const float* sap = SA + ((c - 1) & 1) * 256 + row8;
;         f32x4 nw, nkka, nk, nwr; float nvA, nvB, nsA, nsB; f32x2 ncc;
;     ...
;         Y_LOAD(0)
;         float ykA = 0.f, ykB = 0.f;
; #pragma unroll
;         for (int q = 0; q < 16; q++) {
;           const f32x4 cw = nw, ckka = nkka, ck = nk, cwr = nwr; const float cvA = nvA, cvB = nvB, psA = nsA, psB = nsB; const f32x2 ccc = ncc;
;           if (q < 15) Y_LOAD(q + 1)
;           __builtin_amdgcn_sched_barrier(0);
;           float nA0 = mul_s(a0, cwr.x), nA1 = mul_s(a2, cwr.z), nB0 = mul_s(b0, cwr.x), nB1 = mul_s(b2, cwr.z);
	v_fma_f32 v4, -v94, v72, v96
	v_fma_f32 v5, -v94, v73, v97
	v_fma_f32 v6, -v94, v74, v98
	v_fma_f32 v7, -v94, v75, v99
	v_add_f32_dpp v102, v102, v102 row_ror:8 row_mask:0xf bank_mask:0x3
	s_nop 1
	v_add_f32_dpp v102, v105, v105 row_ror:8 row_mask:0xf bank_mask:0xc
	ds_read_b128 v[64:67], v0 offset:35968
	ds_read_b128 v[68:71], v0 offset:36224
	ds_read_b128 v[76:79], v0 offset:36736
	ds_read_b128 v[60:63], v0 offset:35712
	ds_read_b128 v[72:75], v0 offset:36480
	s_waitcnt lgkmcnt(8)
	v_mul_f32_e32 v88, v4, v44
	v_mul_f32_e32 v89, v6, v48
	v_fma_f32 v88, v5, v46, v88
	v_fma_f32 v89, v7, v50, v89
	v_mul_f32_e32 v90, v4, v45
	v_add_f32_e32 v92, v88, v89
	v_mul_f32_e32 v91, v6, v49
	v_fma_f32 v90, v5, v47, v90
	v_add_f32_dpp v93, v92, v92 quad_perm:[1,0,3,2] row_mask:0xf bank_mask:0xf
	v_fma_f32 v91, v7, v51, v91
	s_waitcnt lgkmcnt(7)
	v_mul_f32_e32 v96, v82, v56
	v_add_f32_dpp v92, v93, v93 quad_perm:[2,3,0,1] row_mask:0xf bank_mask:0xf
	v_mul_f32_e32 v97, v82, v57
	v_mul_f32_e32 v98, v82, v58
	v_add_f32_dpp v93, v92, v92 row_ror:4 row_mask:0xf bank_mask:0xf
	v_mul_f32_e32 v99, v82, v59
	s_waitcnt lgkmcnt(6)
	v_fma_f32 v96, v4, v40, v96
	v_fma_f32 v97, v5, v41, v97
	v_add_f32_dpp v94, v93, v93 row_ror:8 row_mask:0xf bank_mask:0xf
	v_add_f32_dpp v110, v93, v93 row_ror:8 row_mask:0xf bank_mask:0x2
	v_fma_f32 v98, v6, v42, v98
	v_fma_f32 v99, v7, v43, v99
	v_add_f32_e32 v103, v90, v91
	s_waitcnt lgkmcnt(5)
	v_fma_f32 v4, -v94, v52, v96
	v_fma_f32 v5, -v94, v53, v97
	v_fma_f32 v6, -v94, v54, v98
	v_fma_f32 v7, -v94, v55, v99
	ds_read_b128 v[44:47], v0 offset:37248
	ds_read_b128 v[48:51], v0 offset:37504
	ds_read_b128 v[56:59], v0 offset:38016
	ds_read_b128 v[40:43], v0 offset:36992
	ds_read_b128 v[52:55], v0 offset:37760
	ds_read_b128 v[84:87], v1 offset:21680
	s_waitcnt lgkmcnt(9)
	v_mul_f32_e32 v88, v4, v64
	v_mul_f32_e32 v89, v6, v68
	v_fma_f32 v88, v5, v66, v88
	v_fma_f32 v89, v7, v70, v89
	v_mul_f32_e32 v90, v4, v65
	v_add_f32_e32 v92, v88, v89
	v_mul_f32_e32 v91, v6, v69
	v_fma_f32 v90, v5, v67, v90
	v_add_f32_dpp v93, v92, v92 quad_perm:[1,0,3,2] row_mask:0xf bank_mask:0xf
	v_fma_f32 v91, v7, v71, v91
	s_waitcnt lgkmcnt(8)
	v_mul_f32_e32 v96, v83, v76
	v_add_f32_dpp v92, v93, v93 quad_perm:[2,3,0,1] row_mask:0xf bank_mask:0xf
	v_mul_f32_e32 v97, v83, v77
	v_mul_f32_e32 v98, v83, v78
	v_add_f32_dpp v93, v92, v92 row_ror:4 row_mask:0xf bank_mask:0xf
	v_mul_f32_e32 v99, v83, v79
	s_waitcnt lgkmcnt(7)
	v_fma_f32 v96, v4, v60, v96
	v_fma_f32 v97, v5, v61, v97
	v_add_f32_dpp v94, v93, v93 row_ror:8 row_mask:0xf bank_mask:0xf
	v_add_f32_dpp v110, v93, v93 row_ror:8 row_mask:0xf bank_mask:0x8
	v_fma_f32 v98, v6, v62, v98
	v_fma_f32 v99, v7, v63, v99
	v_add_f32_e32 v101, v90, v91
	s_waitcnt lgkmcnt(6)
	v_fma_f32 v4, -v94, v72, v96
	v_fma_f32 v5, -v94, v73, v97
	v_fma_f32 v6, -v94, v74, v98
	v_fma_f32 v7, -v94, v75, v99
	v_add_f32_dpp v103, v103, v103 row_ror:8 row_mask:0xf bank_mask:0x3
	s_nop 1
	v_add_f32_dpp v103, v101, v101 row_ror:8 row_mask:0xf bank_mask:0xc
	v_add_f32_dpp v102, v102, v102 row_half_mirror row_mask:0xf bank_mask:0x5
	s_nop 1
	v_add_f32_dpp v102, v103, v103 row_half_mirror row_mask:0xf bank_mask:0xa
	ds_read_b128 v[64:67], v0 offset:38528
	ds_read_b128 v[68:71], v0 offset:38784
	ds_read_b128 v[76:79], v0 offset:39296
	ds_read_b128 v[60:63], v0 offset:38272
	ds_read_b128 v[72:75], v0 offset:39040
	s_waitcnt lgkmcnt(9)
	v_mul_f32_e32 v88, v4, v44
	v_mul_f32_e32 v89, v6, v48
	v_fma_f32 v88, v5, v46, v88
	v_fma_f32 v89, v7, v50, v89
	v_mul_f32_e32 v90, v4, v45
	v_add_f32_e32 v92, v88, v89
	v_mul_f32_e32 v91, v6, v49
	v_fma_f32 v90, v5, v47, v90
	v_add_f32_dpp v93, v92, v92 quad_perm:[1,0,3,2] row_mask:0xf bank_mask:0xf
	v_fma_f32 v91, v7, v51, v91
	s_waitcnt lgkmcnt(5)
	v_mul_f32_e32 v96, v84, v56
	v_add_f32_dpp v92, v93, v93 quad_perm:[2,3,0,1] row_mask:0xf bank_mask:0xf
	v_mul_f32_e32 v97, v84, v57
	v_mul_f32_e32 v98, v84, v58
	v_add_f32_dpp v93, v92, v92 row_ror:4 row_mask:0xf bank_mask:0xf
	v_mul_f32_e32 v99, v84, v59
	v_fma_f32 v96, v4, v40, v96
	v_fma_f32 v97, v5, v41, v97
	v_add_f32_dpp v94, v93, v93 row_ror:8 row_mask:0xf bank_mask:0xf
	v_add_f32_dpp v111, v93, v93 row_ror:8 row_mask:0xf bank_mask:0x1
	v_fma_f32 v98, v6, v42, v98
	v_fma_f32 v99, v7, v43, v99
	v_add_f32_e32 v104, v90, v91
	v_fma_f32 v4, -v94, v52, v96
	v_fma_f32 v5, -v94, v53, v97
	v_fma_f32 v6, -v94, v54, v98
	v_fma_f32 v7, -v94, v55, v99
	ds_read_b128 v[44:47], v0 offset:39808
	ds_read_b128 v[48:51], v0 offset:40064
	ds_read_b128 v[56:59], v0 offset:40576
	ds_read_b128 v[40:43], v0 offset:39552
	ds_read_b128 v[52:55], v0 offset:40320
	s_waitcnt lgkmcnt(8)
	v_mul_f32_e32 v88, v4, v64
	v_mul_f32_e32 v89, v6, v68
	v_fma_f32 v88, v5, v66, v88
	v_fma_f32 v89, v7, v70, v89
	v_mul_f32_e32 v90, v4, v65
	v_add_f32_e32 v92, v88, v89
	v_mul_f32_e32 v91, v6, v69
	v_fma_f32 v90, v5, v67, v90
	v_add_f32_dpp v93, v92, v92 quad_perm:[1,0,3,2] row_mask:0xf bank_mask:0xf
	v_fma_f32 v91, v7, v71, v91
	s_waitcnt lgkmcnt(7)
	v_mul_f32_e32 v96, v85, v76
	v_add_f32_dpp v92, v93, v93 quad_perm:[2,3,0,1] row_mask:0xf bank_mask:0xf
	v_mul_f32_e32 v97, v85, v77
	v_mul_f32_e32 v98, v85, v78
	v_add_f32_dpp v93, v92, v92 row_ror:4 row_mask:0xf bank_mask:0xf
	v_mul_f32_e32 v99, v85, v79
	s_waitcnt lgkmcnt(6)
	v_fma_f32 v96, v4, v60, v96
	v_fma_f32 v97, v5, v61, v97
	v_add_f32_dpp v94, v93, v93 row_ror:8 row_mask:0xf bank_mask:0xf
	v_add_f32_dpp v111, v93, v93 row_ror:8 row_mask:0xf bank_mask:0x4
	v_fma_f32 v98, v6, v62, v98
	v_fma_f32 v99, v7, v63, v99
	v_add_f32_e32 v105, v90, v91
	s_waitcnt lgkmcnt(5)
; __device__ __forceinline__ unsigned char* WS(const Params& p) { unsigned z = 0; asm volatile("" : "+s"(z)); return p.ws + z; }
; __device__ __forceinline__ unsigned short f2bf(float f) { unsigned r; asm("v_cvt_pk_bf16_f32 %0, %1, %1" : "=v"(r) : "v"(f)); return (unsigned short)(r & 0xffffu); }
; __device__ __forceinline__ float fma_s(float a, float b, float c) { float d; asm("v_fma_f32 %0, %1, %2, %3" : "=v"(d) : "v"(a), "v"(b), "v"(c)); return d; }
; __device__ __forceinline__ float fnma_s(float a, float b, float c) { float d; asm("v_fma_f32 %0, -%1, %2, %3" : "=v"(d) : "v"(a), "v"(b), "v"(c)); return d; }
; __device__ __forceinline__ float sel_eq(float keep, float v, int a, int b) { asm("v_cmp_eq_u32 vcc, %1, %2\n\tv_cndmask_b32 %0, %0, %3, vcc" : "+v"(keep) : "v"(a), "v"(b), "v"(v) : "vcc"); return keep; }
; __device__ __forceinline__ void rwkv_scan2_item(const Params& p, int item, char* ldsraw) {
;     ...
;           const float yA = fnma_s(psA, ccc.x, fma_s(cvA, ccc.y, puA)), yB = fnma_s(psB, ccc.x, fma_s(cvB, ccc.y, puB));
;           ykA = sel_eq(ykA, yA, jl, q); ykB = sel_eq(ykB, yB, jl, q);
;         }
;     ...
;         yout[(size_t)(c - 1) * ystride] = f2bf(ykA); yout[(size_t)(c - 1) * ystride + 8] = f2bf(ykB);
;       }
;     }
;     if (c + 1 < 128) store(bnext);
;     bi = bnext;
;     asm volatile("s_waitcnt lgkmcnt(0)" ::: "memory"); __builtin_amdgcn_s_barrier(); asm volatile("" ::: "memory");
;   }
;   if (seg == 0 && !isY) {
;     float* sf = (float*)(WS(p) + OFF_SF) + ((size_t)bh * 64 + rowA) * 64 + jl * 4;
;     *(f32x4*)sf = (f32x4){a0, a1, a2, a3}; *(f32x4*)(sf + 8 * 64) = (f32x4){b0, b1, b2, b3};
;   }
	v_fma_f32 v4, -v94, v72, v96
	v_fma_f32 v5, -v94, v73, v97
	v_fma_f32 v6, -v94, v74, v98
	v_fma_f32 v7, -v94, v75, v99
	v_add_f32_dpp v104, v104, v104 row_ror:8 row_mask:0xf bank_mask:0x3
	s_nop 1
	v_add_f32_dpp v104, v105, v105 row_ror:8 row_mask:0xf bank_mask:0xc
	ds_read_b128 v[64:67], v0 offset:41088
	ds_read_b128 v[68:71], v0 offset:41344
	ds_read_b128 v[76:79], v0 offset:41856
	ds_read_b128 v[60:63], v0 offset:40832
	ds_read_b128 v[72:75], v0 offset:41600
	ds_read_b32 v112, v10 offset:21632
	ds_read_b64 v[114:115], v11 offset:21632
	s_waitcnt lgkmcnt(10)
	v_mul_f32_e32 v88, v4, v44
	v_mul_f32_e32 v89, v6, v48
	v_fma_f32 v88, v5, v46, v88
	v_fma_f32 v89, v7, v50, v89
	v_mul_f32_e32 v90, v4, v45
	v_add_f32_e32 v92, v88, v89
	v_mul_f32_e32 v91, v6, v49
	v_fma_f32 v90, v5, v47, v90
	v_add_f32_dpp v93, v92, v92 quad_perm:[1,0,3,2] row_mask:0xf bank_mask:0xf
	v_fma_f32 v91, v7, v51, v91
	s_waitcnt lgkmcnt(9)
	v_mul_f32_e32 v96, v86, v56
	v_add_f32_dpp v92, v93, v93 quad_perm:[2,3,0,1] row_mask:0xf bank_mask:0xf
	v_mul_f32_e32 v97, v86, v57
	v_mul_f32_e32 v98, v86, v58
	v_add_f32_dpp v93, v92, v92 row_ror:4 row_mask:0xf bank_mask:0xf
	v_mul_f32_e32 v99, v86, v59
	s_waitcnt lgkmcnt(8)
	v_fma_f32 v96, v4, v40, v96
	v_fma_f32 v97, v5, v41, v97
	v_add_f32_dpp v94, v93, v93 row_ror:8 row_mask:0xf bank_mask:0xf
	v_add_f32_dpp v111, v93, v93 row_ror:8 row_mask:0xf bank_mask:0x2
	v_fma_f32 v98, v6, v42, v98
	v_fma_f32 v99, v7, v43, v99
	v_add_f32_e32 v101, v90, v91
	s_waitcnt lgkmcnt(7)
	v_fma_f32 v4, -v94, v52, v96
	v_fma_f32 v5, -v94, v53, v97
	v_fma_f32 v6, -v94, v54, v98
	v_fma_f32 v7, -v94, v55, v99
	s_waitcnt lgkmcnt(5)
	v_mul_f32_e32 v88, v4, v64
	v_mul_f32_e32 v89, v6, v68
	v_fma_f32 v88, v5, v66, v88
	v_fma_f32 v89, v7, v70, v89
	v_mul_f32_e32 v90, v4, v65
	v_add_f32_e32 v92, v88, v89
	v_mul_f32_e32 v91, v6, v69
	v_fma_f32 v90, v5, v67, v90
	v_add_f32_dpp v93, v92, v92 quad_perm:[1,0,3,2] row_mask:0xf bank_mask:0xf
	v_fma_f32 v91, v7, v71, v91
	s_waitcnt lgkmcnt(4)
	v_mul_f32_e32 v96, v87, v76
	v_add_f32_dpp v92, v93, v93 quad_perm:[2,3,0,1] row_mask:0xf bank_mask:0xf
	v_mul_f32_e32 v97, v87, v77
	v_mul_f32_e32 v98, v87, v78
	v_add_f32_dpp v93, v92, v92 row_ror:4 row_mask:0xf bank_mask:0xf
	v_mul_f32_e32 v99, v87, v79
	s_waitcnt lgkmcnt(3)
	v_fma_f32 v96, v4, v60, v96
	v_fma_f32 v97, v5, v61, v97
	v_add_f32_dpp v94, v93, v93 row_ror:8 row_mask:0xf bank_mask:0xf
	v_add_f32_dpp v111, v93, v93 row_ror:8 row_mask:0xf bank_mask:0x8
	v_fma_f32 v98, v6, v62, v98
	v_fma_f32 v99, v7, v63, v99
	v_add_f32_e32 v103, v90, v91
	s_waitcnt lgkmcnt(2)
	v_fma_f32 v4, -v94, v72, v96
	v_fma_f32 v5, -v94, v73, v97
	v_fma_f32 v6, -v94, v74, v98
	v_fma_f32 v7, -v94, v75, v99
	v_add_f32_dpp v101, v101, v101 row_ror:8 row_mask:0xf bank_mask:0x3
	s_nop 1
	v_add_f32_dpp v101, v103, v103 row_ror:8 row_mask:0xf bank_mask:0xc
	v_add_f32_dpp v104, v104, v104 row_half_mirror row_mask:0xf bank_mask:0x5
	s_nop 1
	v_add_f32_dpp v104, v101, v101 row_half_mirror row_mask:0xf bank_mask:0xa
	v_cndmask_b32_e64 v106, v104, v102, s[36:37]
	v_cndmask_b32_e64 v107, v102, v104, s[36:37]
	s_nop 1
	v_add_f32_dpp v102, v106, v107 quad_perm:[2,3,0,1] row_mask:0xf bank_mask:0xf
	v_cndmask_b32_e64 v106, v102, v100, s[34:35]
	v_cndmask_b32_e64 v107, v100, v102, s[34:35]
	s_nop 1
	v_add_f32_dpp v100, v106, v107 quad_perm:[1,0,3,2] row_mask:0xf bank_mask:0xf
	v_cndmask_b32_e64 v106, v108, v110, s[34:35]
	v_cndmask_b32_e64 v107, v109, v111, s[34:35]
	v_cndmask_b32_e64 v106, v106, v107, s[36:37]
	s_waitcnt lgkmcnt(0)
	v_fma_f32 v100, v112, v115, v100
	v_fma_f32 v100, -v106, v114, v100
	v_cvt_pk_bf16_f32 v107, v100, v100
	global_store_short v16, v107, s[30:31]
	s_cmp_eq_u32 s38, 63
	s_cbranch_scc1 .Lsc_o_nost
	s_waitcnt vmcnt(1)
	ds_write_b128 v2, v[20:23] offset:0
	v_lshlrev_b32_e32 v36, 16, v24
	v_lshlrev_b32_e32 v37, 16, v30
	v_and_b32_e32 v38, 0xffff0000, v24
	v_and_b32_e32 v39, 0xffff0000, v30
	ds_write_b128 v2, v[36:39] offset:256
	v_lshlrev_b32_e32 v40, 16, v25
	v_lshlrev_b32_e32 v41, 16, v31
	v_and_b32_e32 v42, 0xffff0000, v25
	v_and_b32_e32 v43, 0xffff0000, v31
	ds_write_b128 v2, v[40:43] offset:512
	v_lshlrev_b32_e32 v44, 16, v26
	v_and_b32_e32 v45, 0xffff0000, v26
	v_lshlrev_b32_e32 v46, 16, v27
	v_and_b32_e32 v47, 0xffff0000, v27
	ds_write_b128 v2, v[44:47] offset:768
	v_lshlrev_b32_e32 v48, 16, v28
	v_and_b32_e32 v49, 0xffff0000, v28
	v_lshlrev_b32_e32 v50, 16, v29
	v_and_b32_e32 v51, 0xffff0000, v29
	ds_write_b128 v2, v[48:51] offset:1024
	v_lshlrev_b32_e32 v52, 16, v32
	s_cmp_eq_u32 s41, 2
	s_cselect_b32 s2, 0, -1
	v_and_b32_e32 v52, s2, v52
	ds_write_b32 v8, v52 offset:0
	s_mov_b32 s2, 0x00010001
	s_mov_b32 s3, 0x00010001
	s_mov_b64 exec, s[2:3]
	ds_write_b64 v9, v[34:35] offset:0
	s_mov_b64 exec, -1
.Lsc_o_nost:
	s_add_u32 s24, s24, 0x1000
	s_addc_u32 s25, s25, 0
	s_add_u32 s26, s26, 0x2800
	s_addc_u32 s27, s27, 0
	s_add_u32 s28, s28, 0x100
	s_addc_u32 s29, s29, 0
	s_add_u32 s30, s30, s40
	s_addc_u32 s31, s31, 0
	s_waitcnt lgkmcnt(0)
	s_barrier
	s_add_u32 s38, s38, 1
	s_cmp_lt_u32 s38, 64
	s_cbranch_scc1 .Lsc_loop
	s_cmp_lg_u32 s41, 0
	s_cbranch_scc1 .Lsc_done
	s_mul_i32 s2, s78, 0xaaab
	s_lshr_b32 s2, s2, 19
	s_lshl_b32 s2, s2, 14
	s_add_u32 s2, s2, 0xff4c000
	s_add_u32 s2, s46, s2
	s_addc_u32 s3, s47, 0
	v_lshl_add_u32 v17, v18, 8, v0
	s_nop 4
	global_store_dwordx4 v17, v[4:7], s[2:3]
.Lsc_done:
	s_waitcnt vmcnt(0) lgkmcnt(0)
	s_branch .LBB0_157
